# baseline (speedup 1.0000x reference)
; #define PG8_STAGE(bufoff, gbase, voff) do { _Pragma("unroll") for (int _i = 0; _i < 2; ++_i) \
;         __builtin_amdgcn_global_load_lds((const unsigned*)((const char*)(gbase) + (voff)[_i]), (LAS unsigned*)(lds + (bufoff) + ldsw + _i * 8192), 16, 0, 0); } while (0)
; #define PG8_LDA(dst, b, h) do { _Pragma("unroll") for (int m = 0; m < 4; ++m) _Pragma("unroll") for (int k = 0; k < 2; ++k) dst[m][k] = *(const LAS bf16x8*)(lds + PG8_SA(b, h) + aoff + m * 2048 + k * 1024); } while (0)
; #define PG8_LDB(dst, b, h) do { _Pragma("unroll") for (int n = 0; n < 2; ++n) _Pragma("unroll") for (int k = 0; k < 2; ++k) dst[n][k] = *(const LAS bf16x8*)(lds + PG8_SB(b, h) + boff + n * 2048 + k * 1024); } while (0)
; #define PG8_WAIT_V(n) asm volatile("s_waitcnt vmcnt(" #n ")" ::: "memory")
; #define PG8_WAIT_L(n) asm volatile("s_waitcnt lgkmcnt(" #n ")" ::: "memory")
; #define PG8_BAR __builtin_amdgcn_s_barrier()
; #define PG8_SCHED __builtin_amdgcn_sched_barrier(0)
; template <class Epi, class Sched, bool FUSED = false, bool APERM = false>
; __device__ __forceinline__ void gemm_phase(int wid_s, LAS unsigned char* lds, const Gemm g, const Sched& S, const Epi& E) {
;     ...
;             const bool last = (t == nt - 2);
;             const char* a1 = cA + (size_t)(t + 1) * kstep;
;             const char* a2 = last ? nA : cA + (size_t)(t + 2) * kstep; const char* b2 = last ? nB : cB + (size_t)(t + 2) * kstep;
;             const char* a3 = a2 + kstep; const char* b3 = b2 + kstep;
;             if (last && has_next) S.a_ready(nxt);
;             PG8_LDB(B0, 0, 0); PG8_LDB(B1, 0, 1); PG8_SCHED; PG8_LDA(At, 0, 0); PG8_STAGE(PG8_SA(1, 1), a1 + hstep, voffA);
;             PG8_WAIT_V(8); PG8_WAIT_L(0); PG8_BAR; PG8_MMA(0, 0, At, B0); PG8_MMA(0, 1, At, B1); PG8_BAR; PG8_SCHED;
;             PG8_LDA(At, 0, 1); PG8_STAGE(PG8_SB(0, 0), b2, voffB); PG8_STAGE(PG8_SB(0, 1), b2 + hstep, voffB); PG8_STAGE(PG8_SA(0, 0), a2, voffA);
;             PG8_WAIT_V(8); PG8_WAIT_L(0); PG8_BAR; PG8_MMA(1, 0, At, B0); PG8_MMA(1, 1, At, B1); PG8_BAR; PG8_SCHED;
.LBB0_145:
	s_add_u32 s42, s40, 0xfff80080
	s_addc_u32 s43, s41, -1
	s_add_i32 s68, 0, 0x10000
	s_cmp_eq_u32 s67, 28
	s_cselect_b32 s45, s3, s43
	s_cselect_b32 s44, s10, s42
	s_cselect_b32 s43, s25, s66
	s_cselect_b32 s42, s27, s35
	s_add_i32 s70, 0, 0x14000
	v_add_u32_e32 v144, s68, v227
	v_add_u32_e32 v160, s70, v227
	ds_read_b128 v[132:135], v144
	ds_read_b128 v[136:139], v144 offset:1024
	ds_read_b128 v[140:143], v144 offset:2048
	ds_read_b128 v[144:147], v144 offset:3072
	ds_read_b128 v[148:151], v160
	ds_read_b128 v[152:155], v160 offset:1024
	ds_read_b128 v[156:159], v160 offset:2048
	ds_read_b128 v[160:163], v160 offset:3072
	v_lshl_add_u64 v[214:215], s[40:41], 0, v[212:213]
	s_add_i32 m0, s52, 0xc000
	ds_read_b128 v[164:167], v228
	ds_read_b128 v[168:171], v228 offset:1024
	ds_read_b128 v[172:175], v228 offset:2048
	ds_read_b128 v[176:179], v228 offset:3072
	ds_read_b128 v[180:183], v228 offset:4096
	ds_read_b128 v[184:187], v228 offset:5120
	ds_read_b128 v[188:191], v228 offset:6144
	ds_read_b128 v[192:195], v228 offset:7168
	global_load_lds_dwordx4 v[214:215], off
	v_lshl_add_u64 v[214:215], s[40:41], 0, v[210:211]
	s_add_i32 m0, s52, 0xe000
	s_nop 0
	global_load_lds_dwordx4 v[214:215], off
	s_waitcnt vmcnt(8)
	s_waitcnt lgkmcnt(0)
	v_mfma_f32_16x16x32_f16 v[128:131], v[132:135], v[164:167], v[128:131]
	v_mfma_f32_16x16x32_f16 v[124:127], v[140:143], v[164:167], v[124:127]
	v_mfma_f32_16x16x32_f16 v[112:115], v[132:135], v[172:175], v[112:115]
	v_mfma_f32_16x16x32_f16 v[108:111], v[140:143], v[172:175], v[108:111]
	s_barrier
	s_setprio 1
	v_mfma_f32_16x16x32_f16 v[96:99], v[132:135], v[180:183], v[96:99]
	v_mfma_f32_16x16x32_f16 v[92:95], v[140:143], v[180:183], v[92:95]
	v_mfma_f32_16x16x32_f16 v[80:83], v[132:135], v[188:191], v[80:83]
	v_mfma_f32_16x16x32_f16 v[76:79], v[140:143], v[188:191], v[76:79]
	v_mfma_f32_16x16x32_f16 v[128:131], v[136:139], v[168:171], v[128:131]
	v_mfma_f32_16x16x32_f16 v[124:127], v[144:147], v[168:171], v[124:127]
	v_mfma_f32_16x16x32_f16 v[112:115], v[136:139], v[176:179], v[112:115]
	v_mfma_f32_16x16x32_f16 v[108:111], v[144:147], v[176:179], v[108:111]
	v_mfma_f32_16x16x32_f16 v[96:99], v[136:139], v[184:187], v[96:99]
	v_mfma_f32_16x16x32_f16 v[92:95], v[144:147], v[184:187], v[92:95]
	v_mfma_f32_16x16x32_f16 v[80:83], v[136:139], v[192:195], v[80:83]
	v_mfma_f32_16x16x32_f16 v[76:79], v[144:147], v[192:195], v[76:79]
	v_mfma_f32_16x16x32_f16 v[120:123], v[148:151], v[164:167], v[120:123]
	v_mfma_f32_16x16x32_f16 v[116:119], v[156:159], v[164:167], v[116:119]
	v_mfma_f32_16x16x32_f16 v[104:107], v[148:151], v[172:175], v[104:107]
	v_mfma_f32_16x16x32_f16 v[100:103], v[156:159], v[172:175], v[100:103]
	v_mfma_f32_16x16x32_f16 v[88:91], v[148:151], v[180:183], v[88:91]
	v_mfma_f32_16x16x32_f16 v[84:87], v[156:159], v[180:183], v[84:87]
	v_mfma_f32_16x16x32_f16 v[68:71], v[148:151], v[188:191], v[68:71]
	v_mfma_f32_16x16x32_f16 v[72:75], v[156:159], v[188:191], v[72:75]
	v_mfma_f32_16x16x32_f16 v[120:123], v[152:155], v[168:171], v[120:123]
	v_mfma_f32_16x16x32_f16 v[116:119], v[160:163], v[168:171], v[116:119]
	v_mfma_f32_16x16x32_f16 v[104:107], v[152:155], v[176:179], v[104:107]
	v_mfma_f32_16x16x32_f16 v[100:103], v[160:163], v[176:179], v[100:103]
	v_mfma_f32_16x16x32_f16 v[88:91], v[152:155], v[184:187], v[88:91]
	v_mfma_f32_16x16x32_f16 v[84:87], v[160:163], v[184:187], v[84:87]
	v_mfma_f32_16x16x32_f16 v[68:71], v[152:155], v[192:195], v[68:71]
	v_mfma_f32_16x16x32_f16 v[72:75], v[160:163], v[192:195], v[72:75]
	s_setprio 0
	s_barrier
	s_add_i32 s68, s68, s51
	v_lshl_add_u64 v[214:215], s[42:43], 0, v[0:1]
	s_mov_b32 m0, s68
	ds_read_b128 v[164:167], v228 offset:16384
	ds_read_b128 v[168:171], v228 offset:17408
	ds_read_b128 v[172:175], v228 offset:18432
	ds_read_b128 v[176:179], v228 offset:19456
	ds_read_b128 v[180:183], v228 offset:20480
	ds_read_b128 v[184:187], v228 offset:21504
	ds_read_b128 v[188:191], v228 offset:22528
	ds_read_b128 v[192:195], v228 offset:23552
	global_load_lds_dwordx4 v[214:215], off
	s_add_i32 m0, s68, 0x2000
	s_add_u32 s68, s42, 0x80000
	v_lshl_add_u64 v[216:217], s[42:43], 0, v[208:209]
	s_addc_u32 s69, s43, 0
	s_add_i32 s70, s70, s51
	global_load_lds_dwordx4 v[216:217], off
	v_lshl_add_u64 v[218:219], s[68:69], 0, v[0:1]
	s_mov_b32 m0, s70
	v_lshl_add_u64 v[220:221], s[44:45], 0, v[208:209]
	global_load_lds_dwordx4 v[218:219], off
	v_lshl_add_u64 v[218:219], s[68:69], 0, v[208:209]
	s_add_i32 m0, s70, 0x2000
	s_nop 0
	global_load_lds_dwordx4 v[218:219], off
	v_lshl_add_u64 v[218:219], s[44:45], 0, v[0:1]
	s_mov_b32 m0, s52
	s_nop 0
	global_load_lds_dwordx4 v[218:219], off
	s_mov_b32 m0, s53
	s_nop 0
	global_load_lds_dwordx4 v[220:221], off
	s_waitcnt vmcnt(8)
	s_waitcnt lgkmcnt(0)
	v_mfma_f32_16x16x32_f16 v[64:67], v[132:135], v[164:167], v[64:67]
	v_mfma_f32_16x16x32_f16 v[60:63], v[140:143], v[164:167], v[60:63]
	v_mfma_f32_16x16x32_f16 v[48:51], v[132:135], v[172:175], v[48:51]
	v_mfma_f32_16x16x32_f16 v[44:47], v[140:143], v[172:175], v[44:47]
	s_barrier
; #define PG8_STAGE(bufoff, gbase, voff) do { _Pragma("unroll") for (int _i = 0; _i < 2; ++_i) \
;         __builtin_amdgcn_global_load_lds((const unsigned*)((const char*)(gbase) + (voff)[_i]), (LAS unsigned*)(lds + (bufoff) + ldsw + _i * 8192), 16, 0, 0); } while (0)
; #define PG8_LDA(dst, b, h) do { _Pragma("unroll") for (int m = 0; m < 4; ++m) _Pragma("unroll") for (int k = 0; k < 2; ++k) dst[m][k] = *(const LAS bf16x8*)(lds + PG8_SA(b, h) + aoff + m * 2048 + k * 1024); } while (0)
; #define PG8_LDB(dst, b, h) do { _Pragma("unroll") for (int n = 0; n < 2; ++n) _Pragma("unroll") for (int k = 0; k < 2; ++k) dst[n][k] = *(const LAS bf16x8*)(lds + PG8_SB(b, h) + boff + n * 2048 + k * 1024); } while (0)
; #define PG8_WAIT_V(n) asm volatile("s_waitcnt vmcnt(" #n ")" ::: "memory")
; #define PG8_WAIT_L(n) asm volatile("s_waitcnt lgkmcnt(" #n ")" ::: "memory")
; #define PG8_BAR __builtin_amdgcn_s_barrier()
; #define PG8_SCHED __builtin_amdgcn_sched_barrier(0)
; template <class Epi, class Sched, bool FUSED = false, bool APERM = false>
; __device__ __forceinline__ void gemm_phase(int wid_s, LAS unsigned char* lds, const Gemm g, const Sched& S, const Epi& E) {
;     ...
;             PG8_WAIT_V(8); PG8_WAIT_L(0); PG8_BAR; PG8_MMA(1, 0, At, B0); PG8_MMA(1, 1, At, B1); PG8_BAR; PG8_SCHED;
;             PG8_LDB(B0, 1, 0); PG8_LDB(B1, 1, 1); PG8_SCHED; PG8_LDA(At, 1, 0); PG8_STAGE(PG8_SA(0, 1), a2 + hstep, voffA);
;             PG8_WAIT_V(8); PG8_WAIT_L(0); PG8_BAR; PG8_MMA(0, 0, At, B0); PG8_MMA(0, 1, At, B1); PG8_BAR; PG8_SCHED;
	s_setprio 1
	v_mfma_f32_16x16x32_f16 v[32:35], v[132:135], v[180:183], v[32:35]
	v_mfma_f32_16x16x32_f16 v[28:31], v[140:143], v[180:183], v[28:31]
	v_mfma_f32_16x16x32_f16 v[12:15], v[132:135], v[188:191], v[12:15]
	v_mfma_f32_16x16x32_f16 v[16:19], v[140:143], v[188:191], v[16:19]
	v_mfma_f32_16x16x32_f16 v[64:67], v[136:139], v[168:171], v[64:67]
	v_mfma_f32_16x16x32_f16 v[60:63], v[144:147], v[168:171], v[60:63]
	v_mfma_f32_16x16x32_f16 v[48:51], v[136:139], v[176:179], v[48:51]
	v_mfma_f32_16x16x32_f16 v[44:47], v[144:147], v[176:179], v[44:47]
	v_mfma_f32_16x16x32_f16 v[32:35], v[136:139], v[184:187], v[32:35]
	v_mfma_f32_16x16x32_f16 v[28:31], v[144:147], v[184:187], v[28:31]
	v_mfma_f32_16x16x32_f16 v[12:15], v[136:139], v[192:195], v[12:15]
	v_mfma_f32_16x16x32_f16 v[16:19], v[144:147], v[192:195], v[16:19]
	v_mfma_f32_16x16x32_f16 v[56:59], v[148:151], v[164:167], v[56:59]
	v_mfma_f32_16x16x32_f16 v[52:55], v[156:159], v[164:167], v[52:55]
	v_mfma_f32_16x16x32_f16 v[40:43], v[148:151], v[172:175], v[40:43]
	v_mfma_f32_16x16x32_f16 v[36:39], v[156:159], v[172:175], v[36:39]
	v_mfma_f32_16x16x32_f16 v[24:27], v[148:151], v[180:183], v[24:27]
	v_mfma_f32_16x16x32_f16 v[20:23], v[156:159], v[180:183], v[20:23]
	v_mfma_f32_16x16x32_f16 v[4:7], v[148:151], v[188:191], v[4:7]
	v_mfma_f32_16x16x32_f16 v[8:11], v[156:159], v[188:191], v[8:11]
	v_mfma_f32_16x16x32_f16 v[56:59], v[152:155], v[168:171], v[56:59]
	v_mfma_f32_16x16x32_f16 v[52:55], v[160:163], v[168:171], v[52:55]
	v_mfma_f32_16x16x32_f16 v[40:43], v[152:155], v[176:179], v[40:43]
	v_mfma_f32_16x16x32_f16 v[36:39], v[160:163], v[176:179], v[36:39]
	v_mfma_f32_16x16x32_f16 v[24:27], v[152:155], v[184:187], v[24:27]
	v_mfma_f32_16x16x32_f16 v[20:23], v[160:163], v[184:187], v[20:23]
	v_mfma_f32_16x16x32_f16 v[4:7], v[152:155], v[192:195], v[4:7]
	v_mfma_f32_16x16x32_f16 v[8:11], v[160:163], v[192:195], v[8:11]
	s_setprio 0
	s_barrier
	s_add_i32 s68, 0, 0x18000
	s_add_i32 s69, 0, 0x1c000
	v_add_u32_e32 v144, s68, v227
	v_add_u32_e32 v160, s69, v227
	ds_read_b128 v[132:135], v144
	ds_read_b128 v[136:139], v144 offset:1024
	ds_read_b128 v[140:143], v144 offset:2048
	ds_read_b128 v[144:147], v144 offset:3072
	ds_read_b128 v[148:151], v160
	ds_read_b128 v[152:155], v160 offset:1024
	ds_read_b128 v[156:159], v160 offset:2048
	ds_read_b128 v[160:163], v160 offset:3072
	s_add_u32 s44, s44, 0x80000
	s_addc_u32 s45, s45, 0
	s_mov_b32 m0, s54
	v_lshl_add_u64 v[222:223], s[44:45], 0, v[0:1]
	ds_read_b128 v[164:167], v228 offset:32768
	ds_read_b128 v[168:171], v228 offset:33792
	ds_read_b128 v[172:175], v228 offset:34816
	ds_read_b128 v[176:179], v228 offset:35840
	ds_read_b128 v[180:183], v228 offset:36864
	ds_read_b128 v[184:187], v228 offset:37888
	ds_read_b128 v[188:191], v228 offset:38912
	ds_read_b128 v[192:195], v228 offset:39936
	global_load_lds_dwordx4 v[222:223], off
	v_lshl_add_u64 v[222:223], s[44:45], 0, v[208:209]
	s_mov_b32 m0, s55
	s_nop 0
	global_load_lds_dwordx4 v[222:223], off
	s_waitcnt vmcnt(8)
	s_waitcnt lgkmcnt(0)
	v_mfma_f32_16x16x32_f16 v[128:131], v[132:135], v[164:167], v[128:131]
	v_mfma_f32_16x16x32_f16 v[124:127], v[140:143], v[164:167], v[124:127]
	v_mfma_f32_16x16x32_f16 v[112:115], v[132:135], v[172:175], v[112:115]
	v_mfma_f32_16x16x32_f16 v[108:111], v[140:143], v[172:175], v[108:111]
	s_barrier
	s_setprio 1
	v_mfma_f32_16x16x32_f16 v[96:99], v[132:135], v[180:183], v[96:99]
	v_mfma_f32_16x16x32_f16 v[92:95], v[140:143], v[180:183], v[92:95]
	v_mfma_f32_16x16x32_f16 v[80:83], v[132:135], v[188:191], v[80:83]
	v_mfma_f32_16x16x32_f16 v[76:79], v[140:143], v[188:191], v[76:79]
	v_mfma_f32_16x16x32_f16 v[128:131], v[136:139], v[168:171], v[128:131]
	v_mfma_f32_16x16x32_f16 v[124:127], v[144:147], v[168:171], v[124:127]
	v_mfma_f32_16x16x32_f16 v[112:115], v[136:139], v[176:179], v[112:115]
	v_mfma_f32_16x16x32_f16 v[108:111], v[144:147], v[176:179], v[108:111]
	v_mfma_f32_16x16x32_f16 v[96:99], v[136:139], v[184:187], v[96:99]
	v_mfma_f32_16x16x32_f16 v[92:95], v[144:147], v[184:187], v[92:95]
	v_mfma_f32_16x16x32_f16 v[80:83], v[136:139], v[192:195], v[80:83]
	v_mfma_f32_16x16x32_f16 v[76:79], v[144:147], v[192:195], v[76:79]
	v_mfma_f32_16x16x32_f16 v[120:123], v[148:151], v[164:167], v[120:123]
	v_mfma_f32_16x16x32_f16 v[116:119], v[156:159], v[164:167], v[116:119]
	v_mfma_f32_16x16x32_f16 v[104:107], v[148:151], v[172:175], v[104:107]
	v_mfma_f32_16x16x32_f16 v[100:103], v[156:159], v[172:175], v[100:103]
	v_mfma_f32_16x16x32_f16 v[88:91], v[148:151], v[180:183], v[88:91]
	v_mfma_f32_16x16x32_f16 v[84:87], v[156:159], v[180:183], v[84:87]
	v_mfma_f32_16x16x32_f16 v[68:71], v[148:151], v[188:191], v[68:71]
	v_mfma_f32_16x16x32_f16 v[72:75], v[156:159], v[188:191], v[72:75]
	v_mfma_f32_16x16x32_f16 v[120:123], v[152:155], v[168:171], v[120:123]
	v_mfma_f32_16x16x32_f16 v[116:119], v[160:163], v[168:171], v[116:119]
	v_mfma_f32_16x16x32_f16 v[104:107], v[152:155], v[176:179], v[104:107]
	v_mfma_f32_16x16x32_f16 v[100:103], v[160:163], v[176:179], v[100:103]
	v_mfma_f32_16x16x32_f16 v[88:91], v[152:155], v[184:187], v[88:91]
	v_mfma_f32_16x16x32_f16 v[84:87], v[160:163], v[184:187], v[84:87]
	v_mfma_f32_16x16x32_f16 v[68:71], v[152:155], v[192:195], v[68:71]
	v_mfma_f32_16x16x32_f16 v[72:75], v[160:163], v[192:195], v[72:75]
	s_setprio 0
	s_barrier
; #define PG8_STAGE(bufoff, gbase, voff) do { _Pragma("unroll") for (int _i = 0; _i < 2; ++_i) \
;         __builtin_amdgcn_global_load_lds((const unsigned*)((const char*)(gbase) + (voff)[_i]), (LAS unsigned*)(lds + (bufoff) + ldsw + _i * 8192), 16, 0, 0); } while (0)
; #define PG8_LDA(dst, b, h) do { _Pragma("unroll") for (int m = 0; m < 4; ++m) _Pragma("unroll") for (int k = 0; k < 2; ++k) dst[m][k] = *(const LAS bf16x8*)(lds + PG8_SA(b, h) + aoff + m * 2048 + k * 1024); } while (0)
; #define PG8_WAIT_V(n) asm volatile("s_waitcnt vmcnt(" #n ")" ::: "memory")
; #define PG8_WAIT_L(n) asm volatile("s_waitcnt lgkmcnt(" #n ")" ::: "memory")
; #define PG8_BAR __builtin_amdgcn_s_barrier()
; #define PG8_SCHED __builtin_amdgcn_sched_barrier(0)
; template <class Epi, class Sched, bool FUSED = false, bool APERM = false>
; __device__ __forceinline__ void gemm_phase(int wid_s, LAS unsigned char* lds, const Gemm g, const Sched& S, const Epi& E) {
;     ...
;             PG8_LDA(At, 1, 1); PG8_STAGE(PG8_SB(1, 0), b3, voffB); PG8_STAGE(PG8_SB(1, 1), b3 + hstep, voffB); PG8_STAGE(PG8_SA(1, 0), a3, voffA);
;             PG8_WAIT_V(8); PG8_WAIT_L(0); PG8_BAR; PG8_MMA(1, 0, At, B0); PG8_MMA(1, 1, At, B1); PG8_BAR; PG8_SCHED;
;         }
;         if (wr == 0) PG8_BAR;
	s_add_i32 s44, s68, s51
	v_lshl_add_u64 v[214:215], v[214:215], 0, s[12:13]
	s_mov_b32 m0, s44
	ds_read_b128 v[164:167], v228 offset:49152
	ds_read_b128 v[168:171], v228 offset:50176
	ds_read_b128 v[172:175], v228 offset:51200
	ds_read_b128 v[176:179], v228 offset:52224
	ds_read_b128 v[180:183], v228 offset:53248
	ds_read_b128 v[184:187], v228 offset:54272
	ds_read_b128 v[188:191], v228 offset:55296
	ds_read_b128 v[192:195], v228 offset:56320
	global_load_lds_dwordx4 v[214:215], off
	s_add_i32 m0, s44, 0x2000
	s_add_u32 s42, s42, 0x80080
	v_lshl_add_u64 v[214:215], v[216:217], 0, s[12:13]
	s_addc_u32 s43, s43, 0
	s_add_i32 s44, s69, s51
	global_load_lds_dwordx4 v[214:215], off
	v_lshl_add_u64 v[214:215], s[42:43], 0, v[0:1]
	s_mov_b32 m0, s44
	s_nop 0
	global_load_lds_dwordx4 v[214:215], off
	v_lshl_add_u64 v[214:215], s[42:43], 0, v[208:209]
	s_add_i32 m0, s44, 0x2000
	s_nop 0
	global_load_lds_dwordx4 v[214:215], off
	v_lshl_add_u64 v[214:215], v[218:219], 0, s[12:13]
	s_mov_b32 m0, s59
	s_nop 0
	global_load_lds_dwordx4 v[214:215], off
	v_lshl_add_u64 v[214:215], v[220:221], 0, s[12:13]
	s_mov_b32 m0, s60
	s_nop 0
	global_load_lds_dwordx4 v[214:215], off
	s_waitcnt vmcnt(8)
	s_waitcnt lgkmcnt(0)
	v_mfma_f32_16x16x32_f16 v[64:67], v[132:135], v[164:167], v[64:67]
	v_mfma_f32_16x16x32_f16 v[60:63], v[140:143], v[164:167], v[60:63]
	v_mfma_f32_16x16x32_f16 v[48:51], v[132:135], v[172:175], v[48:51]
	v_mfma_f32_16x16x32_f16 v[44:47], v[140:143], v[172:175], v[44:47]
	s_barrier
	s_setprio 1
	v_mfma_f32_16x16x32_f16 v[32:35], v[132:135], v[180:183], v[32:35]
	v_mfma_f32_16x16x32_f16 v[28:31], v[140:143], v[180:183], v[28:31]
	v_mfma_f32_16x16x32_f16 v[12:15], v[132:135], v[188:191], v[12:15]
	v_mfma_f32_16x16x32_f16 v[16:19], v[140:143], v[188:191], v[16:19]
	v_mfma_f32_16x16x32_f16 v[64:67], v[136:139], v[168:171], v[64:67]
	v_mfma_f32_16x16x32_f16 v[60:63], v[144:147], v[168:171], v[60:63]
	v_mfma_f32_16x16x32_f16 v[48:51], v[136:139], v[176:179], v[48:51]
	v_mfma_f32_16x16x32_f16 v[44:47], v[144:147], v[176:179], v[44:47]
	v_mfma_f32_16x16x32_f16 v[32:35], v[136:139], v[184:187], v[32:35]
	v_mfma_f32_16x16x32_f16 v[28:31], v[144:147], v[184:187], v[28:31]
	v_mfma_f32_16x16x32_f16 v[12:15], v[136:139], v[192:195], v[12:15]
	v_mfma_f32_16x16x32_f16 v[16:19], v[144:147], v[192:195], v[16:19]
	v_mfma_f32_16x16x32_f16 v[56:59], v[148:151], v[164:167], v[56:59]
	v_mfma_f32_16x16x32_f16 v[52:55], v[156:159], v[164:167], v[52:55]
	v_mfma_f32_16x16x32_f16 v[40:43], v[148:151], v[172:175], v[40:43]
	v_mfma_f32_16x16x32_f16 v[36:39], v[156:159], v[172:175], v[36:39]
	v_mfma_f32_16x16x32_f16 v[24:27], v[148:151], v[180:183], v[24:27]
	v_mfma_f32_16x16x32_f16 v[20:23], v[156:159], v[180:183], v[20:23]
	v_mfma_f32_16x16x32_f16 v[4:7], v[148:151], v[188:191], v[4:7]
	v_mfma_f32_16x16x32_f16 v[8:11], v[156:159], v[188:191], v[8:11]
	v_mfma_f32_16x16x32_f16 v[56:59], v[152:155], v[168:171], v[56:59]
	v_mfma_f32_16x16x32_f16 v[52:55], v[160:163], v[168:171], v[52:55]
	v_mfma_f32_16x16x32_f16 v[40:43], v[152:155], v[176:179], v[40:43]
	v_mfma_f32_16x16x32_f16 v[36:39], v[160:163], v[176:179], v[36:39]
	v_mfma_f32_16x16x32_f16 v[24:27], v[152:155], v[184:187], v[24:27]
	v_mfma_f32_16x16x32_f16 v[20:23], v[160:163], v[184:187], v[20:23]
	v_mfma_f32_16x16x32_f16 v[4:7], v[152:155], v[192:195], v[4:7]
	v_mfma_f32_16x16x32_f16 v[8:11], v[160:163], v[192:195], v[8:11]
	s_setprio 0
	s_barrier
	s_add_i32 s67, s67, 2
	s_add_u32 s35, s35, 0x100
	s_addc_u32 s66, s66, 0
	s_add_u32 s40, s40, 0x100
	s_addc_u32 s41, s41, 0
	s_cmp_gt_u32 s67, 29
	s_cbranch_scc0 .LBB0_145
	s_and_b64 vcc, exec, s[16:17]
	s_cbranch_vccz .LBB0_148
	s_barrier

; #define PG8_STAGE(bufoff, gbase, voff) do { _Pragma("unroll") for (int _i = 0; _i < 2; ++_i) \
;         __builtin_amdgcn_global_load_lds((const unsigned*)((const char*)(gbase) + (voff)[_i]), (LAS unsigned*)(lds + (bufoff) + ldsw + _i * 8192), 16, 0, 0); } while (0)
; #define PG8_LDA(dst, b, h) do { _Pragma("unroll") for (int m = 0; m < 4; ++m) _Pragma("unroll") for (int k = 0; k < 2; ++k) dst[m][k] = *(const LAS bf16x8*)(lds + PG8_SA(b, h) + aoff + m * 2048 + k * 1024); } while (0)
; #define PG8_LDB(dst, b, h) do { _Pragma("unroll") for (int n = 0; n < 2; ++n) _Pragma("unroll") for (int k = 0; k < 2; ++k) dst[n][k] = *(const LAS bf16x8*)(lds + PG8_SB(b, h) + boff + n * 2048 + k * 1024); } while (0)
; #define PG8_WAIT_V(n) asm volatile("s_waitcnt vmcnt(" #n ")" ::: "memory")
; #define PG8_WAIT_L(n) asm volatile("s_waitcnt lgkmcnt(" #n ")" ::: "memory")
; #define PG8_BAR __builtin_amdgcn_s_barrier()
; #define PG8_SCHED __builtin_amdgcn_sched_barrier(0)
; template <class Epi, class Sched, bool FUSED = false, bool APERM = false>
; __device__ __forceinline__ void gemm_phase(int wid_s, LAS unsigned char* lds, const Gemm g, const Sched& S, const Epi& E) {
;     ...
;             const bool last = (t == nt - 2);
;             const char* a1 = cA + (size_t)(t + 1) * kstep;
;             const char* a2 = last ? nA : cA + (size_t)(t + 2) * kstep; const char* b2 = last ? nB : cB + (size_t)(t + 2) * kstep;
;             const char* a3 = a2 + kstep; const char* b3 = b2 + kstep;
;             if (last && has_next) S.a_ready(nxt);
;             PG8_LDB(B0, 0, 0); PG8_LDB(B1, 0, 1); PG8_SCHED; PG8_LDA(At, 0, 0); PG8_STAGE(PG8_SA(1, 1), a1 + hstep, voffA);
;             PG8_WAIT_V(8); PG8_WAIT_L(0); PG8_BAR; PG8_MMA(0, 0, At, B0); PG8_MMA(0, 1, At, B1); PG8_BAR; PG8_SCHED;
;             PG8_LDA(At, 0, 1); PG8_STAGE(PG8_SB(0, 0), b2, voffB); PG8_STAGE(PG8_SB(0, 1), b2 + hstep, voffB); PG8_STAGE(PG8_SA(0, 0), a2, voffA);
;             PG8_WAIT_V(8); PG8_WAIT_L(0); PG8_BAR; PG8_MMA(1, 0, At, B0); PG8_MMA(1, 1, At, B1); PG8_BAR; PG8_SCHED;
.LBB0_653:
	s_add_u32 s38, s28, s36
	s_addc_u32 s39, s29, s37
	s_add_u32 s38, s38, 0x100
	s_addc_u32 s39, s39, 0
	s_add_u32 s63, s58, s36
	s_addc_u32 s64, s59, s37
	s_add_i32 s65, 0, 0x10000
	s_cmpk_eq_i32 s36, 0xf00
	s_cselect_b32 s41, s27, s39
	s_cselect_b32 s40, s60, s38
	v_add_u32_e32 v143, s65, v3
	s_cselect_b32 s39, s25, s64
	s_cselect_b32 s38, s61, s63
	s_add_i32 s63, 0, 0x14000
	ds_read_b128 v[144:147], v143
	ds_read_b128 v[148:151], v143 offset:1024
	ds_read_b128 v[152:155], v143 offset:2048
	ds_read_b128 v[156:159], v143 offset:3072
	v_add_u32_e32 v143, s63, v3
	ds_read_b128 v[160:163], v143
	ds_read_b128 v[164:167], v143 offset:1024
	ds_read_b128 v[168:171], v143 offset:2048
	ds_read_b128 v[172:175], v143 offset:3072
	v_lshl_add_u64 v[222:223], v[140:141], 0, s[36:37]
	s_add_i32 m0, s15, 0xc000
	ds_read_b128 v[176:179], v142
	ds_read_b128 v[180:183], v142 offset:1024
	ds_read_b128 v[184:187], v142 offset:2048
	ds_read_b128 v[188:191], v142 offset:3072
	ds_read_b128 v[192:195], v142 offset:4096
	ds_read_b128 v[208:211], v142 offset:5120
	ds_read_b128 v[212:215], v142 offset:6144
	ds_read_b128 v[216:219], v142 offset:7168
	global_load_lds_dwordx4 v[222:223], off
	v_lshl_add_u64 v[222:223], v[138:139], 0, s[36:37]
	s_add_i32 m0, s15, 0xe000
	s_nop 0
	global_load_lds_dwordx4 v[222:223], off
	s_waitcnt vmcnt(8)
	s_waitcnt lgkmcnt(0)
	v_mfma_f32_16x16x32_f16 v[128:131], v[144:147], v[176:179], v[128:131]
	v_mfma_f32_16x16x32_f16 v[124:127], v[152:155], v[176:179], v[124:127]
	v_mfma_f32_16x16x32_f16 v[112:115], v[144:147], v[184:187], v[112:115]
	v_mfma_f32_16x16x32_f16 v[108:111], v[152:155], v[184:187], v[108:111]
	s_barrier
	s_setprio 1
	v_mfma_f32_16x16x32_f16 v[96:99], v[144:147], v[192:195], v[96:99]
	v_mfma_f32_16x16x32_f16 v[92:95], v[152:155], v[192:195], v[92:95]
	v_mfma_f32_16x16x32_f16 v[80:83], v[144:147], v[212:215], v[80:83]
	v_mfma_f32_16x16x32_f16 v[76:79], v[152:155], v[212:215], v[76:79]
	v_mfma_f32_16x16x32_f16 v[128:131], v[148:151], v[180:183], v[128:131]
	v_mfma_f32_16x16x32_f16 v[124:127], v[156:159], v[180:183], v[124:127]
	v_mfma_f32_16x16x32_f16 v[112:115], v[148:151], v[188:191], v[112:115]
	v_mfma_f32_16x16x32_f16 v[108:111], v[156:159], v[188:191], v[108:111]
	v_mfma_f32_16x16x32_f16 v[96:99], v[148:151], v[208:211], v[96:99]
	v_mfma_f32_16x16x32_f16 v[92:95], v[156:159], v[208:211], v[92:95]
	v_mfma_f32_16x16x32_f16 v[80:83], v[148:151], v[216:219], v[80:83]
	v_mfma_f32_16x16x32_f16 v[76:79], v[156:159], v[216:219], v[76:79]
	v_mfma_f32_16x16x32_f16 v[120:123], v[160:163], v[176:179], v[120:123]
	v_mfma_f32_16x16x32_f16 v[116:119], v[168:171], v[176:179], v[116:119]
	v_mfma_f32_16x16x32_f16 v[104:107], v[160:163], v[184:187], v[104:107]
	v_mfma_f32_16x16x32_f16 v[100:103], v[168:171], v[184:187], v[100:103]
	v_mfma_f32_16x16x32_f16 v[88:91], v[160:163], v[192:195], v[88:91]
	v_mfma_f32_16x16x32_f16 v[84:87], v[168:171], v[192:195], v[84:87]
	v_mfma_f32_16x16x32_f16 v[72:75], v[160:163], v[212:215], v[72:75]
	v_mfma_f32_16x16x32_f16 v[68:71], v[168:171], v[212:215], v[68:71]
	v_mfma_f32_16x16x32_f16 v[120:123], v[164:167], v[180:183], v[120:123]
	v_mfma_f32_16x16x32_f16 v[116:119], v[172:175], v[180:183], v[116:119]
	v_mfma_f32_16x16x32_f16 v[104:107], v[164:167], v[188:191], v[104:107]
	v_mfma_f32_16x16x32_f16 v[100:103], v[172:175], v[188:191], v[100:103]
	v_mfma_f32_16x16x32_f16 v[88:91], v[164:167], v[208:211], v[88:91]
	v_mfma_f32_16x16x32_f16 v[84:87], v[172:175], v[208:211], v[84:87]
	v_mfma_f32_16x16x32_f16 v[72:75], v[164:167], v[216:219], v[72:75]
	v_mfma_f32_16x16x32_f16 v[68:71], v[172:175], v[216:219], v[68:71]
	s_setprio 0
	s_barrier
	s_add_i32 s64, s65, s49
	v_lshl_add_u64 v[222:223], s[38:39], 0, v[0:1]
	s_mov_b32 m0, s64
	ds_read_b128 v[176:179], v142 offset:16384
	ds_read_b128 v[180:183], v142 offset:17408
	ds_read_b128 v[184:187], v142 offset:18432
	ds_read_b128 v[188:191], v142 offset:19456
	ds_read_b128 v[192:195], v142 offset:20480
	ds_read_b128 v[208:211], v142 offset:21504
	ds_read_b128 v[212:215], v142 offset:22528
	ds_read_b128 v[216:219], v142 offset:23552
	global_load_lds_dwordx4 v[222:223], off
	s_add_i32 m0, s64, 0x2000
	s_add_u32 s64, s38, 0x80000
	v_lshl_add_u64 v[224:225], s[38:39], 0, v[132:133]
	s_addc_u32 s65, s39, 0
	s_add_i32 s63, s63, s49
	global_load_lds_dwordx4 v[224:225], off
	v_lshl_add_u64 v[226:227], s[64:65], 0, v[0:1]
	s_mov_b32 m0, s63
	v_lshl_add_u64 v[228:229], s[40:41], 0, v[132:133]
	global_load_lds_dwordx4 v[226:227], off
	v_lshl_add_u64 v[226:227], s[64:65], 0, v[132:133]
	s_add_i32 m0, s63, 0x2000
	s_nop 0
	global_load_lds_dwordx4 v[226:227], off
	v_lshl_add_u64 v[226:227], s[40:41], 0, v[0:1]
	s_mov_b32 m0, s15
	s_nop 0
	global_load_lds_dwordx4 v[226:227], off
	s_mov_b32 m0, s50
	s_nop 0
	global_load_lds_dwordx4 v[228:229], off
	s_waitcnt vmcnt(8)
	s_waitcnt lgkmcnt(0)
	v_mfma_f32_16x16x32_f16 v[64:67], v[144:147], v[176:179], v[64:67]
	v_mfma_f32_16x16x32_f16 v[60:63], v[152:155], v[176:179], v[60:63]
	v_mfma_f32_16x16x32_f16 v[48:51], v[144:147], v[184:187], v[48:51]
	v_mfma_f32_16x16x32_f16 v[44:47], v[152:155], v[184:187], v[44:47]
	s_barrier
; #define PG8_STAGE(bufoff, gbase, voff) do { _Pragma("unroll") for (int _i = 0; _i < 2; ++_i) \
;         __builtin_amdgcn_global_load_lds((const unsigned*)((const char*)(gbase) + (voff)[_i]), (LAS unsigned*)(lds + (bufoff) + ldsw + _i * 8192), 16, 0, 0); } while (0)
; #define PG8_LDA(dst, b, h) do { _Pragma("unroll") for (int m = 0; m < 4; ++m) _Pragma("unroll") for (int k = 0; k < 2; ++k) dst[m][k] = *(const LAS bf16x8*)(lds + PG8_SA(b, h) + aoff + m * 2048 + k * 1024); } while (0)
; #define PG8_LDB(dst, b, h) do { _Pragma("unroll") for (int n = 0; n < 2; ++n) _Pragma("unroll") for (int k = 0; k < 2; ++k) dst[n][k] = *(const LAS bf16x8*)(lds + PG8_SB(b, h) + boff + n * 2048 + k * 1024); } while (0)
; #define PG8_WAIT_V(n) asm volatile("s_waitcnt vmcnt(" #n ")" ::: "memory")
; #define PG8_WAIT_L(n) asm volatile("s_waitcnt lgkmcnt(" #n ")" ::: "memory")
; #define PG8_BAR __builtin_amdgcn_s_barrier()
; #define PG8_SCHED __builtin_amdgcn_sched_barrier(0)
; template <class Epi, class Sched, bool FUSED = false, bool APERM = false>
; __device__ __forceinline__ void gemm_phase(int wid_s, LAS unsigned char* lds, const Gemm g, const Sched& S, const Epi& E) {
;     ...
;             PG8_WAIT_V(8); PG8_WAIT_L(0); PG8_BAR; PG8_MMA(1, 0, At, B0); PG8_MMA(1, 1, At, B1); PG8_BAR; PG8_SCHED;
;             PG8_LDB(B0, 1, 0); PG8_LDB(B1, 1, 1); PG8_SCHED; PG8_LDA(At, 1, 0); PG8_STAGE(PG8_SA(0, 1), a2 + hstep, voffA);
;             PG8_WAIT_V(8); PG8_WAIT_L(0); PG8_BAR; PG8_MMA(0, 0, At, B0); PG8_MMA(0, 1, At, B1); PG8_BAR; PG8_SCHED;
	s_setprio 1
	v_mfma_f32_16x16x32_f16 v[32:35], v[144:147], v[192:195], v[32:35]
	v_mfma_f32_16x16x32_f16 v[28:31], v[152:155], v[192:195], v[28:31]
	v_mfma_f32_16x16x32_f16 v[16:19], v[144:147], v[212:215], v[16:19]
	v_mfma_f32_16x16x32_f16 v[12:15], v[152:155], v[212:215], v[12:15]
	v_mfma_f32_16x16x32_f16 v[64:67], v[148:151], v[180:183], v[64:67]
	v_mfma_f32_16x16x32_f16 v[60:63], v[156:159], v[180:183], v[60:63]
	v_mfma_f32_16x16x32_f16 v[48:51], v[148:151], v[188:191], v[48:51]
	v_mfma_f32_16x16x32_f16 v[44:47], v[156:159], v[188:191], v[44:47]
	v_mfma_f32_16x16x32_f16 v[32:35], v[148:151], v[208:211], v[32:35]
	v_mfma_f32_16x16x32_f16 v[28:31], v[156:159], v[208:211], v[28:31]
	v_mfma_f32_16x16x32_f16 v[16:19], v[148:151], v[216:219], v[16:19]
	v_mfma_f32_16x16x32_f16 v[12:15], v[156:159], v[216:219], v[12:15]
	v_mfma_f32_16x16x32_f16 v[56:59], v[160:163], v[176:179], v[56:59]
	v_mfma_f32_16x16x32_f16 v[52:55], v[168:171], v[176:179], v[52:55]
	v_mfma_f32_16x16x32_f16 v[40:43], v[160:163], v[184:187], v[40:43]
	v_mfma_f32_16x16x32_f16 v[36:39], v[168:171], v[184:187], v[36:39]
	v_mfma_f32_16x16x32_f16 v[24:27], v[160:163], v[192:195], v[24:27]
	v_mfma_f32_16x16x32_f16 v[20:23], v[168:171], v[192:195], v[20:23]
	v_mfma_f32_16x16x32_f16 v[8:11], v[160:163], v[212:215], v[8:11]
	v_mfma_f32_16x16x32_f16 v[4:7], v[168:171], v[212:215], v[4:7]
	v_mfma_f32_16x16x32_f16 v[56:59], v[164:167], v[180:183], v[56:59]
	v_mfma_f32_16x16x32_f16 v[52:55], v[172:175], v[180:183], v[52:55]
	v_mfma_f32_16x16x32_f16 v[40:43], v[164:167], v[188:191], v[40:43]
	v_mfma_f32_16x16x32_f16 v[36:39], v[172:175], v[188:191], v[36:39]
	v_mfma_f32_16x16x32_f16 v[24:27], v[164:167], v[208:211], v[24:27]
	v_mfma_f32_16x16x32_f16 v[20:23], v[172:175], v[208:211], v[20:23]
	v_mfma_f32_16x16x32_f16 v[8:11], v[164:167], v[216:219], v[8:11]
	v_mfma_f32_16x16x32_f16 v[4:7], v[172:175], v[216:219], v[4:7]
	s_setprio 0
	s_barrier
	s_add_i32 s63, 0, 0x18000
	v_add_u32_e32 v143, s63, v3
	s_add_i32 s64, 0, 0x1c000
	ds_read_b128 v[144:147], v143
	ds_read_b128 v[148:151], v143 offset:1024
	ds_read_b128 v[152:155], v143 offset:2048
	ds_read_b128 v[156:159], v143 offset:3072
	v_add_u32_e32 v143, s64, v3
	ds_read_b128 v[160:163], v143
	ds_read_b128 v[164:167], v143 offset:1024
	ds_read_b128 v[168:171], v143 offset:2048
	ds_read_b128 v[172:175], v143 offset:3072
	s_add_u32 s40, s40, 0x80000
	s_addc_u32 s41, s41, 0
	s_mov_b32 m0, s51
	v_lshl_add_u64 v[230:231], s[40:41], 0, v[0:1]
	ds_read_b128 v[176:179], v142 offset:32768
	ds_read_b128 v[180:183], v142 offset:33792
	ds_read_b128 v[184:187], v142 offset:34816
	ds_read_b128 v[188:191], v142 offset:35840
	ds_read_b128 v[192:195], v142 offset:36864
	ds_read_b128 v[208:211], v142 offset:37888
	ds_read_b128 v[212:215], v142 offset:38912
	ds_read_b128 v[216:219], v142 offset:39936
	global_load_lds_dwordx4 v[230:231], off
	v_lshl_add_u64 v[230:231], s[40:41], 0, v[132:133]
	s_mov_b32 m0, s52
	s_nop 0
	global_load_lds_dwordx4 v[230:231], off
	s_waitcnt vmcnt(8)
	s_waitcnt lgkmcnt(0)
	v_mfma_f32_16x16x32_f16 v[128:131], v[144:147], v[176:179], v[128:131]
	v_mfma_f32_16x16x32_f16 v[124:127], v[152:155], v[176:179], v[124:127]
	v_mfma_f32_16x16x32_f16 v[112:115], v[144:147], v[184:187], v[112:115]
	v_mfma_f32_16x16x32_f16 v[108:111], v[152:155], v[184:187], v[108:111]
	s_barrier
	s_setprio 1
	v_mfma_f32_16x16x32_f16 v[96:99], v[144:147], v[192:195], v[96:99]
	v_mfma_f32_16x16x32_f16 v[92:95], v[152:155], v[192:195], v[92:95]
	v_mfma_f32_16x16x32_f16 v[80:83], v[144:147], v[212:215], v[80:83]
	v_mfma_f32_16x16x32_f16 v[76:79], v[152:155], v[212:215], v[76:79]
	v_mfma_f32_16x16x32_f16 v[128:131], v[148:151], v[180:183], v[128:131]
	v_mfma_f32_16x16x32_f16 v[124:127], v[156:159], v[180:183], v[124:127]
	v_mfma_f32_16x16x32_f16 v[112:115], v[148:151], v[188:191], v[112:115]
	v_mfma_f32_16x16x32_f16 v[108:111], v[156:159], v[188:191], v[108:111]
	v_mfma_f32_16x16x32_f16 v[96:99], v[148:151], v[208:211], v[96:99]
	v_mfma_f32_16x16x32_f16 v[92:95], v[156:159], v[208:211], v[92:95]
	v_mfma_f32_16x16x32_f16 v[80:83], v[148:151], v[216:219], v[80:83]
	v_mfma_f32_16x16x32_f16 v[76:79], v[156:159], v[216:219], v[76:79]
	v_mfma_f32_16x16x32_f16 v[120:123], v[160:163], v[176:179], v[120:123]
	v_mfma_f32_16x16x32_f16 v[116:119], v[168:171], v[176:179], v[116:119]
	v_mfma_f32_16x16x32_f16 v[104:107], v[160:163], v[184:187], v[104:107]
	v_mfma_f32_16x16x32_f16 v[100:103], v[168:171], v[184:187], v[100:103]
	v_mfma_f32_16x16x32_f16 v[88:91], v[160:163], v[192:195], v[88:91]
	v_mfma_f32_16x16x32_f16 v[84:87], v[168:171], v[192:195], v[84:87]
	v_mfma_f32_16x16x32_f16 v[72:75], v[160:163], v[212:215], v[72:75]
	v_mfma_f32_16x16x32_f16 v[68:71], v[168:171], v[212:215], v[68:71]
	v_mfma_f32_16x16x32_f16 v[120:123], v[164:167], v[180:183], v[120:123]
	v_mfma_f32_16x16x32_f16 v[116:119], v[172:175], v[180:183], v[116:119]
	v_mfma_f32_16x16x32_f16 v[104:107], v[164:167], v[188:191], v[104:107]
	v_mfma_f32_16x16x32_f16 v[100:103], v[172:175], v[188:191], v[100:103]
	v_mfma_f32_16x16x32_f16 v[88:91], v[164:167], v[208:211], v[88:91]
	v_mfma_f32_16x16x32_f16 v[84:87], v[172:175], v[208:211], v[84:87]
	v_mfma_f32_16x16x32_f16 v[72:75], v[164:167], v[216:219], v[72:75]
	v_mfma_f32_16x16x32_f16 v[68:71], v[172:175], v[216:219], v[68:71]
	s_setprio 0
	s_barrier
; #define PG8_STAGE(bufoff, gbase, voff) do { _Pragma("unroll") for (int _i = 0; _i < 2; ++_i) \
;         __builtin_amdgcn_global_load_lds((const unsigned*)((const char*)(gbase) + (voff)[_i]), (LAS unsigned*)(lds + (bufoff) + ldsw + _i * 8192), 16, 0, 0); } while (0)
; #define PG8_LDA(dst, b, h) do { _Pragma("unroll") for (int m = 0; m < 4; ++m) _Pragma("unroll") for (int k = 0; k < 2; ++k) dst[m][k] = *(const LAS bf16x8*)(lds + PG8_SA(b, h) + aoff + m * 2048 + k * 1024); } while (0)
; #define PG8_WAIT_V(n) asm volatile("s_waitcnt vmcnt(" #n ")" ::: "memory")
; #define PG8_WAIT_L(n) asm volatile("s_waitcnt lgkmcnt(" #n ")" ::: "memory")
; #define PG8_BAR __builtin_amdgcn_s_barrier()
; #define PG8_SCHED __builtin_amdgcn_sched_barrier(0)
; template <class Epi, class Sched, bool FUSED = false, bool APERM = false>
; __device__ __forceinline__ void gemm_phase(int wid_s, LAS unsigned char* lds, const Gemm g, const Sched& S, const Epi& E) {
;     ...
;             PG8_LDA(At, 1, 1); PG8_STAGE(PG8_SB(1, 0), b3, voffB); PG8_STAGE(PG8_SB(1, 1), b3 + hstep, voffB); PG8_STAGE(PG8_SA(1, 0), a3, voffA);
;             PG8_WAIT_V(8); PG8_WAIT_L(0); PG8_BAR; PG8_MMA(1, 0, At, B0); PG8_MMA(1, 1, At, B1); PG8_BAR; PG8_SCHED;
;         }
;         if (wr == 0) PG8_BAR;
	s_add_i32 s40, s63, s49
	v_lshl_add_u64 v[222:223], v[222:223], 0, s[12:13]
	s_mov_b32 m0, s40
	ds_read_b128 v[176:179], v142 offset:49152
	ds_read_b128 v[180:183], v142 offset:50176
	ds_read_b128 v[184:187], v142 offset:51200
	ds_read_b128 v[188:191], v142 offset:52224
	ds_read_b128 v[192:195], v142 offset:53248
	ds_read_b128 v[208:211], v142 offset:54272
	ds_read_b128 v[212:215], v142 offset:55296
	ds_read_b128 v[216:219], v142 offset:56320
	global_load_lds_dwordx4 v[222:223], off
	s_add_i32 m0, s40, 0x2000
	s_add_u32 s38, s38, 0x80080
	v_lshl_add_u64 v[222:223], v[224:225], 0, s[12:13]
	s_addc_u32 s39, s39, 0
	s_add_i32 s40, s64, s49
	global_load_lds_dwordx4 v[222:223], off
	v_lshl_add_u64 v[222:223], s[38:39], 0, v[0:1]
	s_mov_b32 m0, s40
	s_nop 0
	global_load_lds_dwordx4 v[222:223], off
	v_lshl_add_u64 v[222:223], s[38:39], 0, v[132:133]
	s_add_i32 m0, s40, 0x2000
	s_nop 0
	global_load_lds_dwordx4 v[222:223], off
	v_lshl_add_u64 v[222:223], v[226:227], 0, s[12:13]
	s_mov_b32 m0, s54
	s_nop 0
	global_load_lds_dwordx4 v[222:223], off
	v_lshl_add_u64 v[222:223], v[228:229], 0, s[12:13]
	s_mov_b32 m0, s55
	s_nop 0
	global_load_lds_dwordx4 v[222:223], off
	s_waitcnt vmcnt(8)
	s_waitcnt lgkmcnt(0)
	v_mfma_f32_16x16x32_f16 v[64:67], v[144:147], v[176:179], v[64:67]
	v_mfma_f32_16x16x32_f16 v[60:63], v[152:155], v[176:179], v[60:63]
	v_mfma_f32_16x16x32_f16 v[48:51], v[144:147], v[184:187], v[48:51]
	v_mfma_f32_16x16x32_f16 v[44:47], v[152:155], v[184:187], v[44:47]
	s_barrier
	s_setprio 1
	v_mfma_f32_16x16x32_f16 v[32:35], v[144:147], v[192:195], v[32:35]
	v_mfma_f32_16x16x32_f16 v[28:31], v[152:155], v[192:195], v[28:31]
	v_mfma_f32_16x16x32_f16 v[16:19], v[144:147], v[212:215], v[16:19]
	v_mfma_f32_16x16x32_f16 v[12:15], v[152:155], v[212:215], v[12:15]
	v_mfma_f32_16x16x32_f16 v[64:67], v[148:151], v[180:183], v[64:67]
	v_mfma_f32_16x16x32_f16 v[60:63], v[156:159], v[180:183], v[60:63]
	v_mfma_f32_16x16x32_f16 v[48:51], v[148:151], v[188:191], v[48:51]
	v_mfma_f32_16x16x32_f16 v[44:47], v[156:159], v[188:191], v[44:47]
	v_mfma_f32_16x16x32_f16 v[32:35], v[148:151], v[208:211], v[32:35]
	v_mfma_f32_16x16x32_f16 v[28:31], v[156:159], v[208:211], v[28:31]
	v_mfma_f32_16x16x32_f16 v[16:19], v[148:151], v[216:219], v[16:19]
	v_mfma_f32_16x16x32_f16 v[12:15], v[156:159], v[216:219], v[12:15]
	v_mfma_f32_16x16x32_f16 v[56:59], v[160:163], v[176:179], v[56:59]
	v_mfma_f32_16x16x32_f16 v[52:55], v[168:171], v[176:179], v[52:55]
	v_mfma_f32_16x16x32_f16 v[40:43], v[160:163], v[184:187], v[40:43]
	v_mfma_f32_16x16x32_f16 v[36:39], v[168:171], v[184:187], v[36:39]
	v_mfma_f32_16x16x32_f16 v[24:27], v[160:163], v[192:195], v[24:27]
	v_mfma_f32_16x16x32_f16 v[20:23], v[168:171], v[192:195], v[20:23]
	v_mfma_f32_16x16x32_f16 v[8:11], v[160:163], v[212:215], v[8:11]
	v_mfma_f32_16x16x32_f16 v[4:7], v[168:171], v[212:215], v[4:7]
	v_mfma_f32_16x16x32_f16 v[56:59], v[164:167], v[180:183], v[56:59]
	v_mfma_f32_16x16x32_f16 v[52:55], v[172:175], v[180:183], v[52:55]
	v_mfma_f32_16x16x32_f16 v[40:43], v[164:167], v[188:191], v[40:43]
	v_mfma_f32_16x16x32_f16 v[36:39], v[172:175], v[188:191], v[36:39]
	v_mfma_f32_16x16x32_f16 v[24:27], v[164:167], v[208:211], v[24:27]
	v_mfma_f32_16x16x32_f16 v[20:23], v[172:175], v[208:211], v[20:23]
	v_mfma_f32_16x16x32_f16 v[8:11], v[164:167], v[216:219], v[8:11]
	v_mfma_f32_16x16x32_f16 v[4:7], v[172:175], v[216:219], v[4:7]
	s_setprio 0
	s_barrier
	s_add_i32 s62, s62, 2
	s_add_u32 s36, s36, 0x100
	s_addc_u32 s37, s37, 0
	s_cmp_gt_u32 s62, 29
	s_cbranch_scc0 .LBB0_653
	s_and_b64 vcc, exec, s[22:23]
	s_cbranch_vccz .LBB0_656
	s_barrier

; #define PG8_STAGE(bufoff, gbase, voff) do { _Pragma("unroll") for (int _i = 0; _i < 2; ++_i) \
;         __builtin_amdgcn_global_load_lds((const unsigned*)((const char*)(gbase) + (voff)[_i]), (LAS unsigned*)(lds + (bufoff) + ldsw + _i * 8192), 16, 0, 0); } while (0)
; #define PG8_LDA(dst, b, h) do { _Pragma("unroll") for (int m = 0; m < 4; ++m) _Pragma("unroll") for (int k = 0; k < 2; ++k) dst[m][k] = *(const LAS bf16x8*)(lds + PG8_SA(b, h) + aoff + m * 2048 + k * 1024); } while (0)
; #define PG8_LDB(dst, b, h) do { _Pragma("unroll") for (int n = 0; n < 2; ++n) _Pragma("unroll") for (int k = 0; k < 2; ++k) dst[n][k] = *(const LAS bf16x8*)(lds + PG8_SB(b, h) + boff + n * 2048 + k * 1024); } while (0)
; #define PG8_WAIT_V(n) asm volatile("s_waitcnt vmcnt(" #n ")" ::: "memory")
; #define PG8_WAIT_L(n) asm volatile("s_waitcnt lgkmcnt(" #n ")" ::: "memory")
; #define PG8_BAR __builtin_amdgcn_s_barrier()
; #define PG8_SCHED __builtin_amdgcn_sched_barrier(0)
; template <class Epi, class Sched, bool FUSED = false, bool APERM = false>
; __device__ __forceinline__ void gemm_phase(int wid_s, LAS unsigned char* lds, const Gemm g, const Sched& S, const Epi& E) {
;     ...
;             PG8_LDB(B0, 0, 0); PG8_LDB(B1, 0, 1); PG8_SCHED; PG8_LDA(At, 0, 0); PG8_STAGE(PG8_SA(1, 1), a1 + hstep, voffA);
;             PG8_WAIT_V(8); PG8_WAIT_L(0); PG8_BAR; PG8_MMA(0, 0, At, B0); PG8_MMA(0, 1, At, B1); PG8_BAR; PG8_SCHED;
;             PG8_LDA(At, 0, 1); PG8_STAGE(PG8_SB(0, 0), b2, voffB); PG8_STAGE(PG8_SB(0, 1), b2 + hstep, voffB); PG8_STAGE(PG8_SA(0, 0), a2, voffA);
;             PG8_WAIT_V(8); PG8_WAIT_L(0); PG8_BAR; PG8_MMA(1, 0, At, B0); PG8_MMA(1, 1, At, B1); PG8_BAR; PG8_SCHED;
.LBB0_754:
	s_add_u32 s36, s6, 0x100
	s_addc_u32 s37, s7, 0
	s_add_i32 s45, 0, 0x10000
	s_cmp_eq_u32 s44, 28
	s_cselect_b32 s41, s3, s37
	s_cselect_b32 s40, s5, s36
	s_cselect_b32 s39, s27, s43
	s_cselect_b32 s38, s29, s42
	s_add_i32 s63, 0, 0x14000
	v_add_u32_e32 v80, s45, v244
	v_add_u32_e32 v96, s63, v244
	ds_read_b128 v[68:71], v80
	ds_read_b128 v[72:75], v80 offset:1024
	ds_read_b128 v[76:79], v80 offset:2048
	ds_read_b128 v[80:83], v80 offset:3072
	ds_read_b128 v[84:87], v96
	ds_read_b128 v[88:91], v96 offset:1024
	ds_read_b128 v[92:95], v96 offset:2048
	ds_read_b128 v[96:99], v96 offset:3072
	v_lshl_add_u64 v[200:201], s[6:7], 0, v[216:217]
	s_add_i32 m0, s52, 0xc000
	ds_read_b128 v[164:167], v245
	ds_read_b128 v[168:171], v245 offset:1024
	ds_read_b128 v[172:175], v245 offset:2048
	ds_read_b128 v[176:179], v245 offset:3072
	ds_read_b128 v[180:183], v245 offset:4096
	ds_read_b128 v[184:187], v245 offset:5120
	ds_read_b128 v[188:191], v245 offset:6144
	ds_read_b128 v[192:195], v245 offset:7168
	global_load_lds_dwordx4 v[200:201], off
	v_lshl_add_u64 v[200:201], s[6:7], 0, v[214:215]
	s_add_i32 m0, s52, 0xe000
	s_nop 0
	global_load_lds_dwordx4 v[200:201], off
	s_waitcnt vmcnt(8)
	s_waitcnt lgkmcnt(0)
	v_mfma_f32_16x16x32_f16 v[160:163], v[68:71], v[164:167], v[160:163]
	v_mfma_f32_16x16x32_f16 v[64:67], v[76:79], v[164:167], v[64:67]
	v_mfma_f32_16x16x32_f16 v[148:151], v[68:71], v[172:175], v[148:151]
	v_mfma_f32_16x16x32_f16 v[48:51], v[76:79], v[172:175], v[48:51]
	s_barrier
	s_setprio 1
	v_mfma_f32_16x16x32_f16 v[132:135], v[68:71], v[180:183], v[132:135]
	v_mfma_f32_16x16x32_f16 v[36:39], v[76:79], v[180:183], v[36:39]
	v_mfma_f32_16x16x32_f16 v[144:147], v[68:71], v[188:191], v[144:147]
	v_mfma_f32_16x16x32_f16 v[44:47], v[76:79], v[188:191], v[44:47]
	v_mfma_f32_16x16x32_f16 v[160:163], v[72:75], v[168:171], v[160:163]
	v_mfma_f32_16x16x32_f16 v[64:67], v[80:83], v[168:171], v[64:67]
	v_mfma_f32_16x16x32_f16 v[148:151], v[72:75], v[176:179], v[148:151]
	v_mfma_f32_16x16x32_f16 v[48:51], v[80:83], v[176:179], v[48:51]
	v_mfma_f32_16x16x32_f16 v[132:135], v[72:75], v[184:187], v[132:135]
	v_mfma_f32_16x16x32_f16 v[36:39], v[80:83], v[184:187], v[36:39]
	v_mfma_f32_16x16x32_f16 v[144:147], v[72:75], v[192:195], v[144:147]
	v_mfma_f32_16x16x32_f16 v[44:47], v[80:83], v[192:195], v[44:47]
	v_mfma_f32_16x16x32_f16 v[156:159], v[84:87], v[164:167], v[156:159]
	v_mfma_f32_16x16x32_f16 v[60:63], v[92:95], v[164:167], v[60:63]
	v_mfma_f32_16x16x32_f16 v[152:155], v[84:87], v[172:175], v[152:155]
	v_mfma_f32_16x16x32_f16 v[56:59], v[92:95], v[172:175], v[56:59]
	v_mfma_f32_16x16x32_f16 v[140:143], v[84:87], v[180:183], v[140:143]
	v_mfma_f32_16x16x32_f16 v[40:43], v[92:95], v[180:183], v[40:43]
	v_mfma_f32_16x16x32_f16 v[136:139], v[84:87], v[188:191], v[136:139]
	v_mfma_f32_16x16x32_f16 v[52:55], v[92:95], v[188:191], v[52:55]
	v_mfma_f32_16x16x32_f16 v[156:159], v[88:91], v[168:171], v[156:159]
	v_mfma_f32_16x16x32_f16 v[60:63], v[96:99], v[168:171], v[60:63]
	v_mfma_f32_16x16x32_f16 v[152:155], v[88:91], v[176:179], v[152:155]
	v_mfma_f32_16x16x32_f16 v[56:59], v[96:99], v[176:179], v[56:59]
	v_mfma_f32_16x16x32_f16 v[140:143], v[88:91], v[184:187], v[140:143]
	v_mfma_f32_16x16x32_f16 v[40:43], v[96:99], v[184:187], v[40:43]
	v_mfma_f32_16x16x32_f16 v[136:139], v[88:91], v[192:195], v[136:139]
	v_mfma_f32_16x16x32_f16 v[52:55], v[96:99], v[192:195], v[52:55]
	s_setprio 0
	s_barrier
	s_add_i32 s6, s45, s51
	v_lshl_add_u64 v[200:201], s[38:39], 0, v[208:209]
	s_mov_b32 m0, s6
	ds_read_b128 v[164:167], v245 offset:16384
	ds_read_b128 v[168:171], v245 offset:17408
	ds_read_b128 v[172:175], v245 offset:18432
	ds_read_b128 v[176:179], v245 offset:19456
	ds_read_b128 v[180:183], v245 offset:20480
	ds_read_b128 v[184:187], v245 offset:21504
	ds_read_b128 v[188:191], v245 offset:22528
	ds_read_b128 v[192:195], v245 offset:23552
	global_load_lds_dwordx4 v[200:201], off
	s_add_i32 m0, s6, 0x2000
	s_add_u32 s6, s38, 0x80000
	v_lshl_add_u64 v[234:235], s[38:39], 0, v[212:213]
	s_addc_u32 s7, s39, 0
	s_add_i32 s45, s63, s51
	global_load_lds_dwordx4 v[234:235], off
	v_lshl_add_u64 v[218:219], s[6:7], 0, v[208:209]
	s_mov_b32 m0, s45
	v_lshl_add_u64 v[236:237], s[40:41], 0, v[0:1]
	global_load_lds_dwordx4 v[218:219], off
	v_lshl_add_u64 v[218:219], s[6:7], 0, v[212:213]
	s_add_i32 m0, s45, 0x2000
	v_lshl_add_u64 v[238:239], s[40:41], 0, v[210:211]
	global_load_lds_dwordx4 v[218:219], off
	s_mov_b32 m0, s52
	s_nop 0
	global_load_lds_dwordx4 v[236:237], off
	s_mov_b32 m0, s53
	s_nop 0
	global_load_lds_dwordx4 v[238:239], off
	s_waitcnt vmcnt(8)
	s_waitcnt lgkmcnt(0)
	v_mfma_f32_16x16x32_f16 v[128:131], v[68:71], v[164:167], v[128:131]
	v_mfma_f32_16x16x32_f16 v[32:35], v[76:79], v[164:167], v[32:35]
	v_mfma_f32_16x16x32_f16 v[120:123], v[68:71], v[172:175], v[120:123]
	v_mfma_f32_16x16x32_f16 v[24:27], v[76:79], v[172:175], v[24:27]
	s_barrier
; #define PG8_STAGE(bufoff, gbase, voff) do { _Pragma("unroll") for (int _i = 0; _i < 2; ++_i) \
;         __builtin_amdgcn_global_load_lds((const unsigned*)((const char*)(gbase) + (voff)[_i]), (LAS unsigned*)(lds + (bufoff) + ldsw + _i * 8192), 16, 0, 0); } while (0)
; #define PG8_LDA(dst, b, h) do { _Pragma("unroll") for (int m = 0; m < 4; ++m) _Pragma("unroll") for (int k = 0; k < 2; ++k) dst[m][k] = *(const LAS bf16x8*)(lds + PG8_SA(b, h) + aoff + m * 2048 + k * 1024); } while (0)
; #define PG8_LDB(dst, b, h) do { _Pragma("unroll") for (int n = 0; n < 2; ++n) _Pragma("unroll") for (int k = 0; k < 2; ++k) dst[n][k] = *(const LAS bf16x8*)(lds + PG8_SB(b, h) + boff + n * 2048 + k * 1024); } while (0)
; #define PG8_WAIT_V(n) asm volatile("s_waitcnt vmcnt(" #n ")" ::: "memory")
; #define PG8_WAIT_L(n) asm volatile("s_waitcnt lgkmcnt(" #n ")" ::: "memory")
; #define PG8_BAR __builtin_amdgcn_s_barrier()
; #define PG8_SCHED __builtin_amdgcn_sched_barrier(0)
; template <class Epi, class Sched, bool FUSED = false, bool APERM = false>
; __device__ __forceinline__ void gemm_phase(int wid_s, LAS unsigned char* lds, const Gemm g, const Sched& S, const Epi& E) {
;     ...
;             PG8_WAIT_V(8); PG8_WAIT_L(0); PG8_BAR; PG8_MMA(1, 0, At, B0); PG8_MMA(1, 1, At, B1); PG8_BAR; PG8_SCHED;
;             PG8_LDB(B0, 1, 0); PG8_LDB(B1, 1, 1); PG8_SCHED; PG8_LDA(At, 1, 0); PG8_STAGE(PG8_SA(0, 1), a2 + hstep, voffA);
;             PG8_WAIT_V(8); PG8_WAIT_L(0); PG8_BAR; PG8_MMA(0, 0, At, B0); PG8_MMA(0, 1, At, B1); PG8_BAR; PG8_SCHED;
	s_setprio 1
	v_mfma_f32_16x16x32_f16 v[100:103], v[68:71], v[180:183], v[100:103]
	v_mfma_f32_16x16x32_f16 v[8:11], v[76:79], v[180:183], v[8:11]
	v_mfma_f32_16x16x32_f16 v[112:115], v[68:71], v[188:191], v[112:115]
	v_mfma_f32_16x16x32_f16 v[4:7], v[76:79], v[188:191], v[4:7]
	v_mfma_f32_16x16x32_f16 v[128:131], v[72:75], v[168:171], v[128:131]
	v_mfma_f32_16x16x32_f16 v[32:35], v[80:83], v[168:171], v[32:35]
	v_mfma_f32_16x16x32_f16 v[120:123], v[72:75], v[176:179], v[120:123]
	v_mfma_f32_16x16x32_f16 v[24:27], v[80:83], v[176:179], v[24:27]
	v_mfma_f32_16x16x32_f16 v[100:103], v[72:75], v[184:187], v[100:103]
	v_mfma_f32_16x16x32_f16 v[8:11], v[80:83], v[184:187], v[8:11]
	v_mfma_f32_16x16x32_f16 v[112:115], v[72:75], v[192:195], v[112:115]
	v_mfma_f32_16x16x32_f16 v[4:7], v[80:83], v[192:195], v[4:7]
	v_mfma_f32_16x16x32_f16 v[28:31], v[92:95], v[164:167], v[28:31]
	v_mfma_f32_16x16x32_f16 v[20:23], v[92:95], v[172:175], v[20:23]
	v_mfma_f32_16x16x32_f16 v[16:19], v[92:95], v[180:183], v[16:19]
	v_mfma_f32_16x16x32_f16 v[12:15], v[92:95], v[188:191], v[12:15]
	v_mfma_f32_16x16x32_f16 v[68:71], v[84:87], v[164:167], v[124:127]
	v_mfma_f32_16x16x32_f16 v[28:31], v[96:99], v[168:171], v[28:31]
	v_mfma_f32_16x16x32_f16 v[72:75], v[84:87], v[172:175], v[116:119]
	v_mfma_f32_16x16x32_f16 v[20:23], v[96:99], v[176:179], v[20:23]
	v_mfma_f32_16x16x32_f16 v[76:79], v[84:87], v[180:183], v[108:111]
	v_mfma_f32_16x16x32_f16 v[16:19], v[96:99], v[184:187], v[16:19]
	v_mfma_f32_16x16x32_f16 v[80:83], v[84:87], v[188:191], v[104:107]
	v_mfma_f32_16x16x32_f16 v[12:15], v[96:99], v[192:195], v[12:15]
	v_mfma_f32_16x16x32_f16 v[68:71], v[88:91], v[168:171], v[68:71]
	v_mfma_f32_16x16x32_f16 v[72:75], v[88:91], v[176:179], v[72:75]
	v_mfma_f32_16x16x32_f16 v[76:79], v[88:91], v[184:187], v[76:79]
	v_mfma_f32_16x16x32_f16 v[80:83], v[88:91], v[192:195], v[80:83]
	s_setprio 0
	s_barrier
	s_add_i32 s45, 0, 0x18000
	s_add_i32 s63, 0, 0x1c000
	v_add_u32_e32 v96, s45, v244
	v_add_u32_e32 v104, s63, v244
	ds_read_b128 v[84:87], v96
	ds_read_b128 v[88:91], v96 offset:1024
	ds_read_b128 v[92:95], v96 offset:2048
	ds_read_b128 v[96:99], v96 offset:3072
	ds_read_b128 v[164:167], v104
	ds_read_b128 v[168:171], v104 offset:1024
	ds_read_b128 v[172:175], v104 offset:2048
	ds_read_b128 v[176:179], v104 offset:3072
	s_add_u32 s6, s40, 0x80000
	s_addc_u32 s7, s41, 0
	s_mov_b32 m0, s54
	v_lshl_add_u64 v[218:219], s[6:7], 0, v[0:1]
	ds_read_b128 v[104:107], v245 offset:32768
	ds_read_b128 v[108:111], v245 offset:33792
	ds_read_b128 v[116:119], v245 offset:34816
	ds_read_b128 v[124:127], v245 offset:35840
	ds_read_b128 v[180:183], v245 offset:36864
	ds_read_b128 v[184:187], v245 offset:37888
	ds_read_b128 v[188:191], v245 offset:38912
	ds_read_b128 v[192:195], v245 offset:39936
	global_load_lds_dwordx4 v[218:219], off
	v_lshl_add_u64 v[218:219], s[6:7], 0, v[210:211]
	s_mov_b32 m0, s55
	s_nop 0
	global_load_lds_dwordx4 v[218:219], off
	s_waitcnt vmcnt(8)
	s_waitcnt lgkmcnt(0)
	v_mfma_f32_16x16x32_f16 v[160:163], v[84:87], v[104:107], v[160:163]
	v_mfma_f32_16x16x32_f16 v[64:67], v[92:95], v[104:107], v[64:67]
	v_mfma_f32_16x16x32_f16 v[148:151], v[84:87], v[116:119], v[148:151]
	v_mfma_f32_16x16x32_f16 v[48:51], v[92:95], v[116:119], v[48:51]
	s_barrier
	s_setprio 1
	v_mfma_f32_16x16x32_f16 v[132:135], v[84:87], v[180:183], v[132:135]
	v_mfma_f32_16x16x32_f16 v[36:39], v[92:95], v[180:183], v[36:39]
	v_mfma_f32_16x16x32_f16 v[144:147], v[84:87], v[188:191], v[144:147]
	v_mfma_f32_16x16x32_f16 v[44:47], v[92:95], v[188:191], v[44:47]
	v_mfma_f32_16x16x32_f16 v[160:163], v[88:91], v[108:111], v[160:163]
	v_mfma_f32_16x16x32_f16 v[64:67], v[96:99], v[108:111], v[64:67]
	v_mfma_f32_16x16x32_f16 v[148:151], v[88:91], v[124:127], v[148:151]
	v_mfma_f32_16x16x32_f16 v[48:51], v[96:99], v[124:127], v[48:51]
	v_mfma_f32_16x16x32_f16 v[132:135], v[88:91], v[184:187], v[132:135]
	v_mfma_f32_16x16x32_f16 v[36:39], v[96:99], v[184:187], v[36:39]
	v_mfma_f32_16x16x32_f16 v[144:147], v[88:91], v[192:195], v[144:147]
	v_mfma_f32_16x16x32_f16 v[44:47], v[96:99], v[192:195], v[44:47]
	v_mfma_f32_16x16x32_f16 v[156:159], v[164:167], v[104:107], v[156:159]
	v_mfma_f32_16x16x32_f16 v[60:63], v[172:175], v[104:107], v[60:63]
	v_mfma_f32_16x16x32_f16 v[152:155], v[164:167], v[116:119], v[152:155]
	v_mfma_f32_16x16x32_f16 v[56:59], v[172:175], v[116:119], v[56:59]
	v_mfma_f32_16x16x32_f16 v[140:143], v[164:167], v[180:183], v[140:143]
	v_mfma_f32_16x16x32_f16 v[40:43], v[172:175], v[180:183], v[40:43]
	v_mfma_f32_16x16x32_f16 v[136:139], v[164:167], v[188:191], v[136:139]
	v_mfma_f32_16x16x32_f16 v[52:55], v[172:175], v[188:191], v[52:55]
	v_mfma_f32_16x16x32_f16 v[156:159], v[168:171], v[108:111], v[156:159]
	v_mfma_f32_16x16x32_f16 v[60:63], v[176:179], v[108:111], v[60:63]
	v_mfma_f32_16x16x32_f16 v[152:155], v[168:171], v[124:127], v[152:155]
	v_mfma_f32_16x16x32_f16 v[56:59], v[176:179], v[124:127], v[56:59]
	v_mfma_f32_16x16x32_f16 v[140:143], v[168:171], v[184:187], v[140:143]
	v_mfma_f32_16x16x32_f16 v[40:43], v[176:179], v[184:187], v[40:43]
	v_mfma_f32_16x16x32_f16 v[136:139], v[168:171], v[192:195], v[136:139]
	v_mfma_f32_16x16x32_f16 v[52:55], v[176:179], v[192:195], v[52:55]
	s_setprio 0
	s_barrier
; #define PG8_STAGE(bufoff, gbase, voff) do { _Pragma("unroll") for (int _i = 0; _i < 2; ++_i) \
;         __builtin_amdgcn_global_load_lds((const unsigned*)((const char*)(gbase) + (voff)[_i]), (LAS unsigned*)(lds + (bufoff) + ldsw + _i * 8192), 16, 0, 0); } while (0)
; #define PG8_LDA(dst, b, h) do { _Pragma("unroll") for (int m = 0; m < 4; ++m) _Pragma("unroll") for (int k = 0; k < 2; ++k) dst[m][k] = *(const LAS bf16x8*)(lds + PG8_SA(b, h) + aoff + m * 2048 + k * 1024); } while (0)
; #define PG8_WAIT_V(n) asm volatile("s_waitcnt vmcnt(" #n ")" ::: "memory")
; #define PG8_WAIT_L(n) asm volatile("s_waitcnt lgkmcnt(" #n ")" ::: "memory")
; #define PG8_BAR __builtin_amdgcn_s_barrier()
; #define PG8_SCHED __builtin_amdgcn_sched_barrier(0)
; template <class Epi, class Sched, bool FUSED = false, bool APERM = false>
; __device__ __forceinline__ void gemm_phase(int wid_s, LAS unsigned char* lds, const Gemm g, const Sched& S, const Epi& E) {
;     ...
;             PG8_LDA(At, 1, 1); PG8_STAGE(PG8_SB(1, 0), b3, voffB); PG8_STAGE(PG8_SB(1, 1), b3 + hstep, voffB); PG8_STAGE(PG8_SA(1, 0), a3, voffA);
;             PG8_WAIT_V(8); PG8_WAIT_L(0); PG8_BAR; PG8_MMA(1, 0, At, B0); PG8_MMA(1, 1, At, B1); PG8_BAR; PG8_SCHED;
;         }
;         if (wr == 0) PG8_BAR;
	s_add_i32 s6, s45, s51
	v_lshl_add_u64 v[104:105], v[200:201], 0, s[12:13]
	s_mov_b32 m0, s6
	ds_read_b128 v[180:183], v245 offset:49152
	ds_read_b128 v[184:187], v245 offset:50176
	ds_read_b128 v[188:191], v245 offset:51200
	ds_read_b128 v[192:195], v245 offset:52224
	ds_read_b128 v[218:221], v245 offset:53248
	ds_read_b128 v[222:225], v245 offset:54272
	ds_read_b128 v[226:229], v245 offset:55296
	ds_read_b128 v[230:233], v245 offset:56320
	global_load_lds_dwordx4 v[104:105], off
	s_add_i32 m0, s6, 0x2000
	s_add_u32 s6, s38, 0x80080
	v_lshl_add_u64 v[104:105], v[234:235], 0, s[12:13]
	s_addc_u32 s7, s39, 0
	s_add_i32 s38, s63, s51
	global_load_lds_dwordx4 v[104:105], off
	v_lshl_add_u64 v[104:105], s[6:7], 0, v[208:209]
	s_mov_b32 m0, s38
	s_nop 0
	global_load_lds_dwordx4 v[104:105], off
	v_lshl_add_u64 v[104:105], s[6:7], 0, v[212:213]
	s_add_i32 m0, s38, 0x2000
	s_nop 0
	global_load_lds_dwordx4 v[104:105], off
	v_lshl_add_u64 v[104:105], v[236:237], 0, s[12:13]
	s_mov_b32 m0, s59
	s_nop 0
	global_load_lds_dwordx4 v[104:105], off
	v_lshl_add_u64 v[104:105], v[238:239], 0, s[12:13]
	s_mov_b32 m0, s60
	s_nop 0
	global_load_lds_dwordx4 v[104:105], off
	s_waitcnt vmcnt(8)
	s_waitcnt lgkmcnt(0)
	v_mfma_f32_16x16x32_f16 v[104:107], v[84:87], v[180:183], v[128:131]
	v_mfma_f32_16x16x32_f16 v[128:131], v[88:91], v[184:187], v[104:107]
	v_mfma_f32_16x16x32_f16 v[104:107], v[84:87], v[188:191], v[120:123]
	v_mfma_f32_16x16x32_f16 v[32:35], v[92:95], v[180:183], v[32:35]
	s_barrier
	s_setprio 1
	v_mfma_f32_16x16x32_f16 v[120:123], v[88:91], v[192:195], v[104:107]
	v_mfma_f32_16x16x32_f16 v[24:27], v[92:95], v[188:191], v[24:27]
	v_mfma_f32_16x16x32_f16 v[100:103], v[84:87], v[218:221], v[100:103]
	v_mfma_f32_16x16x32_f16 v[8:11], v[92:95], v[218:221], v[8:11]
	v_mfma_f32_16x16x32_f16 v[104:107], v[84:87], v[226:229], v[112:115]
	v_mfma_f32_16x16x32_f16 v[4:7], v[92:95], v[226:229], v[4:7]
	v_mfma_f32_16x16x32_f16 v[32:35], v[96:99], v[184:187], v[32:35]
	v_mfma_f32_16x16x32_f16 v[24:27], v[96:99], v[192:195], v[24:27]
	v_mfma_f32_16x16x32_f16 v[100:103], v[88:91], v[222:225], v[100:103]
	v_mfma_f32_16x16x32_f16 v[8:11], v[96:99], v[222:225], v[8:11]
	v_mfma_f32_16x16x32_f16 v[112:115], v[88:91], v[230:233], v[104:107]
	v_mfma_f32_16x16x32_f16 v[4:7], v[96:99], v[230:233], v[4:7]
	v_mfma_f32_16x16x32_f16 v[68:71], v[164:167], v[180:183], v[68:71]
	v_mfma_f32_16x16x32_f16 v[124:127], v[168:171], v[184:187], v[68:71]
	v_mfma_f32_16x16x32_f16 v[68:71], v[164:167], v[188:191], v[72:75]
	v_mfma_f32_16x16x32_f16 v[116:119], v[168:171], v[192:195], v[68:71]
	v_mfma_f32_16x16x32_f16 v[68:71], v[164:167], v[218:221], v[76:79]
	v_mfma_f32_16x16x32_f16 v[28:31], v[172:175], v[180:183], v[28:31]
	v_mfma_f32_16x16x32_f16 v[20:23], v[172:175], v[188:191], v[20:23]
	v_mfma_f32_16x16x32_f16 v[108:111], v[168:171], v[222:225], v[68:71]
	v_mfma_f32_16x16x32_f16 v[16:19], v[172:175], v[218:221], v[16:19]
	v_mfma_f32_16x16x32_f16 v[68:71], v[164:167], v[226:229], v[80:83]
	v_mfma_f32_16x16x32_f16 v[12:15], v[172:175], v[226:229], v[12:15]
	v_mfma_f32_16x16x32_f16 v[28:31], v[176:179], v[184:187], v[28:31]
	v_mfma_f32_16x16x32_f16 v[20:23], v[176:179], v[192:195], v[20:23]
	v_mfma_f32_16x16x32_f16 v[16:19], v[176:179], v[222:225], v[16:19]
	v_mfma_f32_16x16x32_f16 v[104:107], v[168:171], v[230:233], v[68:71]
	v_mfma_f32_16x16x32_f16 v[12:15], v[176:179], v[230:233], v[12:15]
	s_setprio 0
	s_barrier
	s_add_i32 s44, s44, 2
	s_add_u32 s42, s42, 0x100
	s_addc_u32 s43, s43, 0
	s_cmp_gt_u32 s44, 29
	s_mov_b64 s[6:7], s[36:37]
	s_cbranch_scc0 .LBB0_754
	s_and_b64 vcc, exec, s[24:25]
	s_cbranch_vccz .LBB0_757
	s_barrier

; #define PG8_STAGE(bufoff, gbase, voff) do { _Pragma("unroll") for (int _i = 0; _i < 2; ++_i) \
;         __builtin_amdgcn_global_load_lds((const unsigned*)((const char*)(gbase) + (voff)[_i]), (LAS unsigned*)(lds + (bufoff) + ldsw + _i * 8192), 16, 0, 0); } while (0)
; #define PG8_LDA(dst, b, h) do { _Pragma("unroll") for (int m = 0; m < 4; ++m) _Pragma("unroll") for (int k = 0; k < 2; ++k) dst[m][k] = *(const LAS bf16x8*)(lds + PG8_SA(b, h) + aoff + m * 2048 + k * 1024); } while (0)
; #define PG8_LDB(dst, b, h) do { _Pragma("unroll") for (int n = 0; n < 2; ++n) _Pragma("unroll") for (int k = 0; k < 2; ++k) dst[n][k] = *(const LAS bf16x8*)(lds + PG8_SB(b, h) + boff + n * 2048 + k * 1024); } while (0)
; #define PG8_WAIT_V(n) asm volatile("s_waitcnt vmcnt(" #n ")" ::: "memory")
; #define PG8_WAIT_L(n) asm volatile("s_waitcnt lgkmcnt(" #n ")" ::: "memory")
; #define PG8_BAR __builtin_amdgcn_s_barrier()
; #define PG8_SCHED __builtin_amdgcn_sched_barrier(0)
; template <class Epi, class Sched, bool FUSED = false, bool APERM = false>
; __device__ __forceinline__ void gemm_phase(int wid_s, LAS unsigned char* lds, const Gemm g, const Sched& S, const Epi& E) {
;     ...
;             const char* a1 = cA + (size_t)(t + 1) * kstep;
;             const char* a2 = last ? nA : cA + (size_t)(t + 2) * kstep; const char* b2 = last ? nB : cB + (size_t)(t + 2) * kstep;
;             const char* a3 = a2 + kstep; const char* b3 = b2 + kstep;
;             if (last && has_next) S.a_ready(nxt);
;             PG8_LDB(B0, 0, 0); PG8_LDB(B1, 0, 1); PG8_SCHED; PG8_LDA(At, 0, 0); PG8_STAGE(PG8_SA(1, 1), a1 + hstep, voffA);
;             PG8_WAIT_V(8); PG8_WAIT_L(0); PG8_BAR; PG8_MMA(0, 0, At, B0); PG8_MMA(0, 1, At, B1); PG8_BAR; PG8_SCHED;
;             PG8_LDA(At, 0, 1); PG8_STAGE(PG8_SB(0, 0), b2, voffB); PG8_STAGE(PG8_SB(0, 1), b2 + hstep, voffB); PG8_STAGE(PG8_SA(0, 0), a2, voffA);
;             PG8_WAIT_V(8); PG8_WAIT_L(0); PG8_BAR; PG8_MMA(1, 0, At, B0); PG8_MMA(1, 1, At, B1); PG8_BAR; PG8_SCHED;
.LBB0_929:
	s_add_u32 s36, s28, s34
	s_addc_u32 s37, s29, s35
	s_add_u32 s36, s36, 0x100
	s_addc_u32 s37, s37, 0
	s_add_u32 s63, s60, s34
	s_addc_u32 s64, s61, s35
	s_add_i32 s65, 0, 0x10000
	s_cmpk_eq_i32 s34, 0x2a00
	s_cselect_b32 s39, s5, s37
	s_cselect_b32 s38, s4, s36
	v_add_u32_e32 v143, s65, v3
	s_cselect_b32 s37, s31, s64
	s_cselect_b32 s36, s30, s63
	s_add_i32 s63, 0, 0x14000
	ds_read_b128 v[144:147], v143
	ds_read_b128 v[148:151], v143 offset:1024
	ds_read_b128 v[152:155], v143 offset:2048
	ds_read_b128 v[156:159], v143 offset:3072
	v_add_u32_e32 v143, s63, v3
	ds_read_b128 v[160:163], v143
	ds_read_b128 v[164:167], v143 offset:1024
	ds_read_b128 v[168:171], v143 offset:2048
	ds_read_b128 v[172:175], v143 offset:3072
	v_lshl_add_u64 v[200:201], v[140:141], 0, s[34:35]
	s_add_i32 m0, s49, 0xc000
	ds_read_b128 v[176:179], v142
	ds_read_b128 v[180:183], v142 offset:1024
	ds_read_b128 v[184:187], v142 offset:2048
	ds_read_b128 v[188:191], v142 offset:3072
	ds_read_b128 v[192:195], v142 offset:4096
	ds_read_b128 v[208:211], v142 offset:5120
	ds_read_b128 v[212:215], v142 offset:6144
	ds_read_b128 v[216:219], v142 offset:7168
	global_load_lds_dwordx4 v[200:201], off
	v_lshl_add_u64 v[200:201], v[138:139], 0, s[34:35]
	s_add_i32 m0, s49, 0xe000
	s_nop 0
	global_load_lds_dwordx4 v[200:201], off
	s_waitcnt vmcnt(8)
	s_waitcnt lgkmcnt(0)
	v_mfma_f32_16x16x32_f16 v[128:131], v[144:147], v[176:179], v[128:131]
	v_mfma_f32_16x16x32_f16 v[124:127], v[152:155], v[176:179], v[124:127]
	v_mfma_f32_16x16x32_f16 v[112:115], v[144:147], v[184:187], v[112:115]
	v_mfma_f32_16x16x32_f16 v[108:111], v[152:155], v[184:187], v[108:111]
	s_barrier
	s_setprio 1
	v_mfma_f32_16x16x32_f16 v[96:99], v[144:147], v[192:195], v[96:99]
	v_mfma_f32_16x16x32_f16 v[92:95], v[152:155], v[192:195], v[92:95]
	v_mfma_f32_16x16x32_f16 v[80:83], v[144:147], v[212:215], v[80:83]
	v_mfma_f32_16x16x32_f16 v[76:79], v[152:155], v[212:215], v[76:79]
	v_mfma_f32_16x16x32_f16 v[128:131], v[148:151], v[180:183], v[128:131]
	v_mfma_f32_16x16x32_f16 v[124:127], v[156:159], v[180:183], v[124:127]
	v_mfma_f32_16x16x32_f16 v[112:115], v[148:151], v[188:191], v[112:115]
	v_mfma_f32_16x16x32_f16 v[108:111], v[156:159], v[188:191], v[108:111]
	v_mfma_f32_16x16x32_f16 v[96:99], v[148:151], v[208:211], v[96:99]
	v_mfma_f32_16x16x32_f16 v[92:95], v[156:159], v[208:211], v[92:95]
	v_mfma_f32_16x16x32_f16 v[80:83], v[148:151], v[216:219], v[80:83]
	v_mfma_f32_16x16x32_f16 v[76:79], v[156:159], v[216:219], v[76:79]
	v_mfma_f32_16x16x32_f16 v[120:123], v[160:163], v[176:179], v[120:123]
	v_mfma_f32_16x16x32_f16 v[116:119], v[168:171], v[176:179], v[116:119]
	v_mfma_f32_16x16x32_f16 v[104:107], v[160:163], v[184:187], v[104:107]
	v_mfma_f32_16x16x32_f16 v[100:103], v[168:171], v[184:187], v[100:103]
	v_mfma_f32_16x16x32_f16 v[88:91], v[160:163], v[192:195], v[88:91]
	v_mfma_f32_16x16x32_f16 v[84:87], v[168:171], v[192:195], v[84:87]
	v_mfma_f32_16x16x32_f16 v[72:75], v[160:163], v[212:215], v[72:75]
	v_mfma_f32_16x16x32_f16 v[68:71], v[168:171], v[212:215], v[68:71]
	v_mfma_f32_16x16x32_f16 v[120:123], v[164:167], v[180:183], v[120:123]
	v_mfma_f32_16x16x32_f16 v[116:119], v[172:175], v[180:183], v[116:119]
	v_mfma_f32_16x16x32_f16 v[104:107], v[164:167], v[188:191], v[104:107]
	v_mfma_f32_16x16x32_f16 v[100:103], v[172:175], v[188:191], v[100:103]
	v_mfma_f32_16x16x32_f16 v[88:91], v[164:167], v[208:211], v[88:91]
	v_mfma_f32_16x16x32_f16 v[84:87], v[172:175], v[208:211], v[84:87]
	v_mfma_f32_16x16x32_f16 v[72:75], v[164:167], v[216:219], v[72:75]
	v_mfma_f32_16x16x32_f16 v[68:71], v[172:175], v[216:219], v[68:71]
	s_setprio 0
	s_barrier
	s_add_i32 s64, s65, s48
	v_lshl_add_u64 v[200:201], s[36:37], 0, v[0:1]
	s_mov_b32 m0, s64
	ds_read_b128 v[176:179], v142 offset:16384
	ds_read_b128 v[180:183], v142 offset:17408
	ds_read_b128 v[184:187], v142 offset:18432
	ds_read_b128 v[188:191], v142 offset:19456
	ds_read_b128 v[192:195], v142 offset:20480
	ds_read_b128 v[208:211], v142 offset:21504
	ds_read_b128 v[212:215], v142 offset:22528
	ds_read_b128 v[216:219], v142 offset:23552
	global_load_lds_dwordx4 v[200:201], off
	s_add_i32 m0, s64, 0x2000
	s_add_u32 s64, s36, 0x158000
	v_lshl_add_u64 v[222:223], s[36:37], 0, v[132:133]
	s_addc_u32 s65, s37, 0
	s_add_i32 s63, s63, s48
	global_load_lds_dwordx4 v[222:223], off
	v_lshl_add_u64 v[224:225], s[64:65], 0, v[0:1]
	s_mov_b32 m0, s63
	v_lshl_add_u64 v[226:227], s[38:39], 0, v[132:133]
	global_load_lds_dwordx4 v[224:225], off
	v_lshl_add_u64 v[224:225], s[64:65], 0, v[132:133]
	s_add_i32 m0, s63, 0x2000
	s_nop 0
	global_load_lds_dwordx4 v[224:225], off
	v_lshl_add_u64 v[224:225], s[38:39], 0, v[0:1]
	s_mov_b32 m0, s49
	s_nop 0
	global_load_lds_dwordx4 v[224:225], off
	s_mov_b32 m0, s50
	s_nop 0
	global_load_lds_dwordx4 v[226:227], off
	s_waitcnt vmcnt(8)
	s_waitcnt lgkmcnt(0)
	v_mfma_f32_16x16x32_f16 v[64:67], v[144:147], v[176:179], v[64:67]
	v_mfma_f32_16x16x32_f16 v[60:63], v[152:155], v[176:179], v[60:63]
	v_mfma_f32_16x16x32_f16 v[48:51], v[144:147], v[184:187], v[48:51]
	v_mfma_f32_16x16x32_f16 v[44:47], v[152:155], v[184:187], v[44:47]
	s_barrier
; #define PG8_STAGE(bufoff, gbase, voff) do { _Pragma("unroll") for (int _i = 0; _i < 2; ++_i) \
;         __builtin_amdgcn_global_load_lds((const unsigned*)((const char*)(gbase) + (voff)[_i]), (LAS unsigned*)(lds + (bufoff) + ldsw + _i * 8192), 16, 0, 0); } while (0)
; #define PG8_LDA(dst, b, h) do { _Pragma("unroll") for (int m = 0; m < 4; ++m) _Pragma("unroll") for (int k = 0; k < 2; ++k) dst[m][k] = *(const LAS bf16x8*)(lds + PG8_SA(b, h) + aoff + m * 2048 + k * 1024); } while (0)
; #define PG8_LDB(dst, b, h) do { _Pragma("unroll") for (int n = 0; n < 2; ++n) _Pragma("unroll") for (int k = 0; k < 2; ++k) dst[n][k] = *(const LAS bf16x8*)(lds + PG8_SB(b, h) + boff + n * 2048 + k * 1024); } while (0)
; #define PG8_WAIT_V(n) asm volatile("s_waitcnt vmcnt(" #n ")" ::: "memory")
; #define PG8_WAIT_L(n) asm volatile("s_waitcnt lgkmcnt(" #n ")" ::: "memory")
; #define PG8_BAR __builtin_amdgcn_s_barrier()
; #define PG8_SCHED __builtin_amdgcn_sched_barrier(0)
; template <class Epi, class Sched, bool FUSED = false, bool APERM = false>
; __device__ __forceinline__ void gemm_phase(int wid_s, LAS unsigned char* lds, const Gemm g, const Sched& S, const Epi& E) {
;     ...
;             PG8_WAIT_V(8); PG8_WAIT_L(0); PG8_BAR; PG8_MMA(1, 0, At, B0); PG8_MMA(1, 1, At, B1); PG8_BAR; PG8_SCHED;
;             PG8_LDB(B0, 1, 0); PG8_LDB(B1, 1, 1); PG8_SCHED; PG8_LDA(At, 1, 0); PG8_STAGE(PG8_SA(0, 1), a2 + hstep, voffA);
;             PG8_WAIT_V(8); PG8_WAIT_L(0); PG8_BAR; PG8_MMA(0, 0, At, B0); PG8_MMA(0, 1, At, B1); PG8_BAR; PG8_SCHED;
	s_setprio 1
	v_mfma_f32_16x16x32_f16 v[32:35], v[144:147], v[192:195], v[32:35]
	v_mfma_f32_16x16x32_f16 v[28:31], v[152:155], v[192:195], v[28:31]
	v_mfma_f32_16x16x32_f16 v[16:19], v[144:147], v[212:215], v[16:19]
	v_mfma_f32_16x16x32_f16 v[12:15], v[152:155], v[212:215], v[12:15]
	v_mfma_f32_16x16x32_f16 v[64:67], v[148:151], v[180:183], v[64:67]
	v_mfma_f32_16x16x32_f16 v[60:63], v[156:159], v[180:183], v[60:63]
	v_mfma_f32_16x16x32_f16 v[48:51], v[148:151], v[188:191], v[48:51]
	v_mfma_f32_16x16x32_f16 v[44:47], v[156:159], v[188:191], v[44:47]
	v_mfma_f32_16x16x32_f16 v[32:35], v[148:151], v[208:211], v[32:35]
	v_mfma_f32_16x16x32_f16 v[28:31], v[156:159], v[208:211], v[28:31]
	v_mfma_f32_16x16x32_f16 v[16:19], v[148:151], v[216:219], v[16:19]
	v_mfma_f32_16x16x32_f16 v[12:15], v[156:159], v[216:219], v[12:15]
	v_mfma_f32_16x16x32_f16 v[56:59], v[160:163], v[176:179], v[56:59]
	v_mfma_f32_16x16x32_f16 v[52:55], v[168:171], v[176:179], v[52:55]
	v_mfma_f32_16x16x32_f16 v[40:43], v[160:163], v[184:187], v[40:43]
	v_mfma_f32_16x16x32_f16 v[36:39], v[168:171], v[184:187], v[36:39]
	v_mfma_f32_16x16x32_f16 v[24:27], v[160:163], v[192:195], v[24:27]
	v_mfma_f32_16x16x32_f16 v[20:23], v[168:171], v[192:195], v[20:23]
	v_mfma_f32_16x16x32_f16 v[8:11], v[160:163], v[212:215], v[8:11]
	v_mfma_f32_16x16x32_f16 v[4:7], v[168:171], v[212:215], v[4:7]
	v_mfma_f32_16x16x32_f16 v[56:59], v[164:167], v[180:183], v[56:59]
	v_mfma_f32_16x16x32_f16 v[52:55], v[172:175], v[180:183], v[52:55]
	v_mfma_f32_16x16x32_f16 v[40:43], v[164:167], v[188:191], v[40:43]
	v_mfma_f32_16x16x32_f16 v[36:39], v[172:175], v[188:191], v[36:39]
	v_mfma_f32_16x16x32_f16 v[24:27], v[164:167], v[208:211], v[24:27]
	v_mfma_f32_16x16x32_f16 v[20:23], v[172:175], v[208:211], v[20:23]
	v_mfma_f32_16x16x32_f16 v[8:11], v[164:167], v[216:219], v[8:11]
	v_mfma_f32_16x16x32_f16 v[4:7], v[172:175], v[216:219], v[4:7]
	s_setprio 0
	s_barrier
	s_add_i32 s63, 0, 0x18000
	v_add_u32_e32 v143, s63, v3
	s_add_i32 s64, 0, 0x1c000
	ds_read_b128 v[144:147], v143
	ds_read_b128 v[148:151], v143 offset:1024
	ds_read_b128 v[152:155], v143 offset:2048
	ds_read_b128 v[156:159], v143 offset:3072
	v_add_u32_e32 v143, s64, v3
	ds_read_b128 v[160:163], v143
	ds_read_b128 v[164:167], v143 offset:1024
	ds_read_b128 v[168:171], v143 offset:2048
	ds_read_b128 v[172:175], v143 offset:3072
	s_add_u32 s38, s38, 0x158000
	s_addc_u32 s39, s39, 0
	s_mov_b32 m0, s51
	v_lshl_add_u64 v[228:229], s[38:39], 0, v[0:1]
	ds_read_b128 v[176:179], v142 offset:32768
	ds_read_b128 v[180:183], v142 offset:33792
	ds_read_b128 v[184:187], v142 offset:34816
	ds_read_b128 v[188:191], v142 offset:35840
	ds_read_b128 v[192:195], v142 offset:36864
	ds_read_b128 v[208:211], v142 offset:37888
	ds_read_b128 v[212:215], v142 offset:38912
	ds_read_b128 v[216:219], v142 offset:39936
	global_load_lds_dwordx4 v[228:229], off
	v_lshl_add_u64 v[228:229], s[38:39], 0, v[132:133]
	s_mov_b32 m0, s52
	s_nop 0
	global_load_lds_dwordx4 v[228:229], off
	s_waitcnt vmcnt(8)
	s_waitcnt lgkmcnt(0)
	v_mfma_f32_16x16x32_f16 v[128:131], v[144:147], v[176:179], v[128:131]
	v_mfma_f32_16x16x32_f16 v[124:127], v[152:155], v[176:179], v[124:127]
	v_mfma_f32_16x16x32_f16 v[112:115], v[144:147], v[184:187], v[112:115]
	v_mfma_f32_16x16x32_f16 v[108:111], v[152:155], v[184:187], v[108:111]
	s_barrier
	s_setprio 1
	v_mfma_f32_16x16x32_f16 v[96:99], v[144:147], v[192:195], v[96:99]
	v_mfma_f32_16x16x32_f16 v[92:95], v[152:155], v[192:195], v[92:95]
	v_mfma_f32_16x16x32_f16 v[80:83], v[144:147], v[212:215], v[80:83]
	v_mfma_f32_16x16x32_f16 v[76:79], v[152:155], v[212:215], v[76:79]
	v_mfma_f32_16x16x32_f16 v[128:131], v[148:151], v[180:183], v[128:131]
	v_mfma_f32_16x16x32_f16 v[124:127], v[156:159], v[180:183], v[124:127]
	v_mfma_f32_16x16x32_f16 v[112:115], v[148:151], v[188:191], v[112:115]
	v_mfma_f32_16x16x32_f16 v[108:111], v[156:159], v[188:191], v[108:111]
	v_mfma_f32_16x16x32_f16 v[96:99], v[148:151], v[208:211], v[96:99]
	v_mfma_f32_16x16x32_f16 v[92:95], v[156:159], v[208:211], v[92:95]
	v_mfma_f32_16x16x32_f16 v[80:83], v[148:151], v[216:219], v[80:83]
	v_mfma_f32_16x16x32_f16 v[76:79], v[156:159], v[216:219], v[76:79]
	v_mfma_f32_16x16x32_f16 v[120:123], v[160:163], v[176:179], v[120:123]
	v_mfma_f32_16x16x32_f16 v[116:119], v[168:171], v[176:179], v[116:119]
	v_mfma_f32_16x16x32_f16 v[104:107], v[160:163], v[184:187], v[104:107]
	v_mfma_f32_16x16x32_f16 v[100:103], v[168:171], v[184:187], v[100:103]
	v_mfma_f32_16x16x32_f16 v[88:91], v[160:163], v[192:195], v[88:91]
	v_mfma_f32_16x16x32_f16 v[84:87], v[168:171], v[192:195], v[84:87]
	v_mfma_f32_16x16x32_f16 v[72:75], v[160:163], v[212:215], v[72:75]
	v_mfma_f32_16x16x32_f16 v[68:71], v[168:171], v[212:215], v[68:71]
	v_mfma_f32_16x16x32_f16 v[120:123], v[164:167], v[180:183], v[120:123]
	v_mfma_f32_16x16x32_f16 v[116:119], v[172:175], v[180:183], v[116:119]
	v_mfma_f32_16x16x32_f16 v[104:107], v[164:167], v[188:191], v[104:107]
	v_mfma_f32_16x16x32_f16 v[100:103], v[172:175], v[188:191], v[100:103]
	v_mfma_f32_16x16x32_f16 v[88:91], v[164:167], v[208:211], v[88:91]
	v_mfma_f32_16x16x32_f16 v[84:87], v[172:175], v[208:211], v[84:87]
	v_mfma_f32_16x16x32_f16 v[72:75], v[164:167], v[216:219], v[72:75]
	v_mfma_f32_16x16x32_f16 v[68:71], v[172:175], v[216:219], v[68:71]
	s_setprio 0
	s_barrier
; #define PG8_STAGE(bufoff, gbase, voff) do { _Pragma("unroll") for (int _i = 0; _i < 2; ++_i) \
;         __builtin_amdgcn_global_load_lds((const unsigned*)((const char*)(gbase) + (voff)[_i]), (LAS unsigned*)(lds + (bufoff) + ldsw + _i * 8192), 16, 0, 0); } while (0)
; #define PG8_LDA(dst, b, h) do { _Pragma("unroll") for (int m = 0; m < 4; ++m) _Pragma("unroll") for (int k = 0; k < 2; ++k) dst[m][k] = *(const LAS bf16x8*)(lds + PG8_SA(b, h) + aoff + m * 2048 + k * 1024); } while (0)
; #define PG8_WAIT_V(n) asm volatile("s_waitcnt vmcnt(" #n ")" ::: "memory")
; #define PG8_WAIT_L(n) asm volatile("s_waitcnt lgkmcnt(" #n ")" ::: "memory")
; #define PG8_BAR __builtin_amdgcn_s_barrier()
; #define PG8_SCHED __builtin_amdgcn_sched_barrier(0)
; template <class Epi, class Sched, bool FUSED = false, bool APERM = false>
; __device__ __forceinline__ void gemm_phase(int wid_s, LAS unsigned char* lds, const Gemm g, const Sched& S, const Epi& E) {
;     ...
;             PG8_LDA(At, 1, 1); PG8_STAGE(PG8_SB(1, 0), b3, voffB); PG8_STAGE(PG8_SB(1, 1), b3 + hstep, voffB); PG8_STAGE(PG8_SA(1, 0), a3, voffA);
;             PG8_WAIT_V(8); PG8_WAIT_L(0); PG8_BAR; PG8_MMA(1, 0, At, B0); PG8_MMA(1, 1, At, B1); PG8_BAR; PG8_SCHED;
;         }
;         if (wr == 0) PG8_BAR;
	s_add_i32 s38, s63, s48
	v_lshl_add_u64 v[200:201], v[200:201], 0, s[12:13]
	s_mov_b32 m0, s38
	ds_read_b128 v[176:179], v142 offset:49152
	ds_read_b128 v[180:183], v142 offset:50176
	ds_read_b128 v[184:187], v142 offset:51200
	ds_read_b128 v[188:191], v142 offset:52224
	ds_read_b128 v[192:195], v142 offset:53248
	ds_read_b128 v[208:211], v142 offset:54272
	ds_read_b128 v[212:215], v142 offset:55296
	ds_read_b128 v[216:219], v142 offset:56320
	global_load_lds_dwordx4 v[200:201], off
	s_add_i32 m0, s38, 0x2000
	s_add_u32 s36, s36, 0x158080
	v_lshl_add_u64 v[200:201], v[222:223], 0, s[12:13]
	s_addc_u32 s37, s37, 0
	s_add_i32 s38, s64, s48
	global_load_lds_dwordx4 v[200:201], off
	v_lshl_add_u64 v[200:201], s[36:37], 0, v[0:1]
	s_mov_b32 m0, s38
	s_nop 0
	global_load_lds_dwordx4 v[200:201], off
	v_lshl_add_u64 v[200:201], s[36:37], 0, v[132:133]
	s_add_i32 m0, s38, 0x2000
	s_nop 0
	global_load_lds_dwordx4 v[200:201], off
	v_lshl_add_u64 v[200:201], v[224:225], 0, s[12:13]
	s_mov_b32 m0, s54
	s_nop 0
	global_load_lds_dwordx4 v[200:201], off
	v_lshl_add_u64 v[200:201], v[226:227], 0, s[12:13]
	s_mov_b32 m0, s55
	s_nop 0
	global_load_lds_dwordx4 v[200:201], off
	s_waitcnt vmcnt(8)
	s_waitcnt lgkmcnt(0)
	v_mfma_f32_16x16x32_f16 v[64:67], v[144:147], v[176:179], v[64:67]
	v_mfma_f32_16x16x32_f16 v[60:63], v[152:155], v[176:179], v[60:63]
	v_mfma_f32_16x16x32_f16 v[48:51], v[144:147], v[184:187], v[48:51]
	v_mfma_f32_16x16x32_f16 v[44:47], v[152:155], v[184:187], v[44:47]
	s_barrier
	s_setprio 1
	v_mfma_f32_16x16x32_f16 v[32:35], v[144:147], v[192:195], v[32:35]
	v_mfma_f32_16x16x32_f16 v[28:31], v[152:155], v[192:195], v[28:31]
	v_mfma_f32_16x16x32_f16 v[16:19], v[144:147], v[212:215], v[16:19]
	v_mfma_f32_16x16x32_f16 v[12:15], v[152:155], v[212:215], v[12:15]
	v_mfma_f32_16x16x32_f16 v[64:67], v[148:151], v[180:183], v[64:67]
	v_mfma_f32_16x16x32_f16 v[60:63], v[156:159], v[180:183], v[60:63]
	v_mfma_f32_16x16x32_f16 v[48:51], v[148:151], v[188:191], v[48:51]
	v_mfma_f32_16x16x32_f16 v[44:47], v[156:159], v[188:191], v[44:47]
	v_mfma_f32_16x16x32_f16 v[32:35], v[148:151], v[208:211], v[32:35]
	v_mfma_f32_16x16x32_f16 v[28:31], v[156:159], v[208:211], v[28:31]
	v_mfma_f32_16x16x32_f16 v[16:19], v[148:151], v[216:219], v[16:19]
	v_mfma_f32_16x16x32_f16 v[12:15], v[156:159], v[216:219], v[12:15]
	v_mfma_f32_16x16x32_f16 v[56:59], v[160:163], v[176:179], v[56:59]
	v_mfma_f32_16x16x32_f16 v[52:55], v[168:171], v[176:179], v[52:55]
	v_mfma_f32_16x16x32_f16 v[40:43], v[160:163], v[184:187], v[40:43]
	v_mfma_f32_16x16x32_f16 v[36:39], v[168:171], v[184:187], v[36:39]
	v_mfma_f32_16x16x32_f16 v[24:27], v[160:163], v[192:195], v[24:27]
	v_mfma_f32_16x16x32_f16 v[20:23], v[168:171], v[192:195], v[20:23]
	v_mfma_f32_16x16x32_f16 v[8:11], v[160:163], v[212:215], v[8:11]
	v_mfma_f32_16x16x32_f16 v[4:7], v[168:171], v[212:215], v[4:7]
	v_mfma_f32_16x16x32_f16 v[56:59], v[164:167], v[180:183], v[56:59]
	v_mfma_f32_16x16x32_f16 v[52:55], v[172:175], v[180:183], v[52:55]
	v_mfma_f32_16x16x32_f16 v[40:43], v[164:167], v[188:191], v[40:43]
	v_mfma_f32_16x16x32_f16 v[36:39], v[172:175], v[188:191], v[36:39]
	v_mfma_f32_16x16x32_f16 v[24:27], v[164:167], v[208:211], v[24:27]
	v_mfma_f32_16x16x32_f16 v[20:23], v[172:175], v[208:211], v[20:23]
	v_mfma_f32_16x16x32_f16 v[8:11], v[164:167], v[216:219], v[8:11]
	v_mfma_f32_16x16x32_f16 v[4:7], v[172:175], v[216:219], v[4:7]
	s_setprio 0
	s_barrier
	s_add_i32 s62, s62, 2
	s_add_u32 s34, s34, 0x100
	s_addc_u32 s35, s35, 0
	s_cmpk_gt_u32 s62, 0x53
	s_cbranch_scc0 .LBB0_929
	s_and_b64 vcc, exec, s[26:27]
	s_cbranch_vccz .LBB0_932
	s_barrier
